# K-loop load segments: fragment reads issued first after the barrier (literal slot offsets), scalar set-up and loop-carried pointer updates moved behind the first read group
# baseline (speedup 1.0000x reference)
.LBB0_231:
	s_ashr_i32 s77, s76, 31
	s_lshl_b64 s[66:67], s[76:77], 19
	s_add_u32 s80, s12, s66
	s_addc_u32 s81, s13, s67
	s_and_b64 s[66:67], s[78:79], exec
	s_cselect_b32 s66, s81, s85
	s_cselect_b32 s67, s80, s84
	s_ashr_i32 s75, s74, 31
	s_lshl_b64 s[68:69], s[74:75], 19
	s_add_u32 s82, s5, s68
	s_addc_u32 s83, s20, s69
	s_and_b64 s[68:69], s[78:79], exec
	s_cselect_b32 s68, s83, s87
	s_cselect_b32 s69, s82, s86
	s_add_u32 s84, s84, 0x40080
	s_addc_u32 s85, s85, 0
	s_add_u32 s75, s86, 0x100
	s_addc_u32 s77, s87, 0
	s_mov_b32 s90, -2
	s_waitcnt vmcnt(0)
	v_add_u32_e32 v160, 0x10000, v145
	v_add_u32_e32 v176, 0x14000, v145
	ds_read_b128 v[140:143], v160
	ds_read_b128 v[152:155], v160 offset:1024
	ds_read_b128 v[156:159], v160 offset:2048
	ds_read_b128 v[160:163], v160 offset:3072
	ds_read_b128 v[164:167], v176
	ds_read_b128 v[168:171], v176 offset:1024
	ds_read_b128 v[172:175], v176 offset:2048
	ds_read_b128 v[176:179], v176 offset:3072
	s_add_u32 s0, s84, 0xfffc0080
	s_addc_u32 s86, s85, -1
	s_add_i32 s96, 0, 0x10000
	s_cmp_eq_u32 s90, 12
	s_cselect_b32 s89, s66, s86
	s_cselect_b32 s88, s67, s0
	s_cselect_b32 s87, s68, s77
	s_cselect_b32 s86, s69, s75
	s_add_i32 s0, 0, 0x14000
	v_lshl_add_u64 v[180:181], s[84:85], 0, v[136:137]
	s_add_i32 m0, s22, 0xc000
	ds_read_b128 v[188:191], v151
	ds_read_b128 v[220:223], v151 offset:1024
	ds_read_b128 v[224:227], v151 offset:2048
	ds_read_b128 v[228:231], v151 offset:3072
	ds_read_b128 v[232:235], v151 offset:4096
	ds_read_b128 v[236:239], v151 offset:5120
	ds_read_b128 v[240:243], v151 offset:6144
	ds_read_b128 v[244:247], v151 offset:7168
	global_load_lds_dwordx4 v[180:181], off
	v_lshl_add_u64 v[180:181], s[84:85], 0, v[138:139]
	s_add_i32 m0, s22, 0xe000
	s_nop 0
	global_load_lds_dwordx4 v[180:181], off
	s_waitcnt vmcnt(8)
	s_waitcnt lgkmcnt(0)
	s_setprio 1
	s_barrier
	v_mfma_f32_16x16x32_bf16 v[128:131], v[140:143], v[188:191], 0
	v_mfma_f32_16x16x32_bf16 v[124:127], v[156:159], v[188:191], 0
	v_mfma_f32_16x16x32_bf16 v[112:115], v[140:143], v[224:227], 0
	v_mfma_f32_16x16x32_bf16 v[108:111], v[156:159], v[224:227], 0
	v_mfma_f32_16x16x32_bf16 v[92:95], v[140:143], v[232:235], 0
	v_mfma_f32_16x16x32_bf16 v[88:91], v[156:159], v[232:235], 0
	v_mfma_f32_16x16x32_bf16 v[76:79], v[140:143], v[240:243], 0
	v_mfma_f32_16x16x32_bf16 v[72:75], v[156:159], v[240:243], 0
	v_mfma_f32_16x16x32_bf16 v[128:131], v[152:155], v[220:223], v[128:131]
	v_mfma_f32_16x16x32_bf16 v[124:127], v[160:163], v[220:223], v[124:127]
	v_mfma_f32_16x16x32_bf16 v[112:115], v[152:155], v[228:231], v[112:115]
	v_mfma_f32_16x16x32_bf16 v[108:111], v[160:163], v[228:231], v[108:111]
	v_mfma_f32_16x16x32_bf16 v[92:95], v[152:155], v[236:239], v[92:95]
	v_mfma_f32_16x16x32_bf16 v[88:91], v[160:163], v[236:239], v[88:91]
	v_mfma_f32_16x16x32_bf16 v[76:79], v[152:155], v[244:247], v[76:79]
	v_mfma_f32_16x16x32_bf16 v[72:75], v[160:163], v[244:247], v[72:75]
	v_mfma_f32_16x16x32_bf16 v[120:123], v[164:167], v[188:191], 0
	v_mfma_f32_16x16x32_bf16 v[116:119], v[172:175], v[188:191], 0
	v_mfma_f32_16x16x32_bf16 v[104:107], v[164:167], v[224:227], 0
	v_mfma_f32_16x16x32_bf16 v[100:103], v[172:175], v[224:227], 0
	v_mfma_f32_16x16x32_bf16 v[84:87], v[164:167], v[232:235], 0
	v_mfma_f32_16x16x32_bf16 v[80:83], v[172:175], v[232:235], 0
	v_mfma_f32_16x16x32_bf16 v[68:71], v[164:167], v[240:243], 0
	v_mfma_f32_16x16x32_bf16 v[64:67], v[172:175], v[240:243], 0
	v_mfma_f32_16x16x32_bf16 v[120:123], v[168:171], v[220:223], v[120:123]
	v_mfma_f32_16x16x32_bf16 v[116:119], v[176:179], v[220:223], v[116:119]
	v_mfma_f32_16x16x32_bf16 v[104:107], v[168:171], v[228:231], v[104:107]
	v_mfma_f32_16x16x32_bf16 v[100:103], v[176:179], v[228:231], v[100:103]
	v_mfma_f32_16x16x32_bf16 v[84:87], v[168:171], v[236:239], v[84:87]
	v_mfma_f32_16x16x32_bf16 v[80:83], v[176:179], v[236:239], v[80:83]
	v_mfma_f32_16x16x32_bf16 v[68:71], v[168:171], v[244:247], v[68:71]
	v_mfma_f32_16x16x32_bf16 v[64:67], v[176:179], v[244:247], v[64:67]
	s_barrier
	s_setprio 0
	ds_read_b128 v[188:191], v151 offset:16384
	ds_read_b128 v[220:223], v151 offset:17408
	ds_read_b128 v[224:227], v151 offset:18432
	ds_read_b128 v[228:231], v151 offset:19456
	ds_read_b128 v[232:235], v151 offset:20480
	ds_read_b128 v[236:239], v151 offset:21504
	ds_read_b128 v[240:243], v151 offset:22528
	ds_read_b128 v[244:247], v151 offset:23552
	s_add_i32 s90, s90, 2
	s_add_u32 s84, s84, 0x100
	s_addc_u32 s85, s85, 0
	s_add_u32 s75, s75, 0x100
	s_addc_u32 s77, s77, 0
	s_add_i32 s96, s96, s1
	s_mov_b32 m0, s96
	v_lshl_add_u64 v[180:181], s[86:87], 0, v[98:99]
	global_load_lds_dwordx4 v[180:181], off
	s_add_i32 m0, s96, 0x2000
	s_add_u32 s96, s86, 0x40000
	v_lshl_add_u64 v[192:193], s[86:87], 0, v[134:135]
	s_addc_u32 s97, s87, 0
	s_add_i32 s0, s0, s1
	global_load_lds_dwordx4 v[192:193], off
	v_lshl_add_u64 v[248:249], s[96:97], 0, v[98:99]
	s_mov_b32 m0, s0
	v_lshl_add_u64 v[250:251], s[88:89], 0, v[132:133]
	global_load_lds_dwordx4 v[248:249], off
	v_lshl_add_u64 v[248:249], s[96:97], 0, v[134:135]
	s_add_i32 m0, s0, 0x2000
	s_nop 0
	global_load_lds_dwordx4 v[248:249], off
	v_lshl_add_u64 v[248:249], s[88:89], 0, v[96:97]
	s_mov_b32 m0, s22
	s_nop 0
	global_load_lds_dwordx4 v[248:249], off
	s_mov_b32 m0, s23
	s_nop 0
	global_load_lds_dwordx4 v[250:251], off
	s_waitcnt vmcnt(8)
	s_waitcnt lgkmcnt(0)
	s_setprio 1
	s_barrier
	v_mfma_f32_16x16x32_bf16 v[60:63], v[140:143], v[188:191], 0
	v_mfma_f32_16x16x32_bf16 v[56:59], v[156:159], v[188:191], 0
	v_mfma_f32_16x16x32_bf16 v[44:47], v[140:143], v[224:227], 0
	v_mfma_f32_16x16x32_bf16 v[40:43], v[156:159], v[224:227], 0
	v_mfma_f32_16x16x32_bf16 v[28:31], v[140:143], v[232:235], 0
	v_mfma_f32_16x16x32_bf16 v[24:27], v[156:159], v[232:235], 0
	v_mfma_f32_16x16x32_bf16 v[12:15], v[140:143], v[240:243], 0
	v_mfma_f32_16x16x32_bf16 v[8:11], v[156:159], v[240:243], 0
	v_mfma_f32_16x16x32_bf16 v[60:63], v[152:155], v[220:223], v[60:63]
	v_mfma_f32_16x16x32_bf16 v[56:59], v[160:163], v[220:223], v[56:59]
	v_mfma_f32_16x16x32_bf16 v[44:47], v[152:155], v[228:231], v[44:47]
	v_mfma_f32_16x16x32_bf16 v[40:43], v[160:163], v[228:231], v[40:43]
	v_mfma_f32_16x16x32_bf16 v[28:31], v[152:155], v[236:239], v[28:31]
	v_mfma_f32_16x16x32_bf16 v[24:27], v[160:163], v[236:239], v[24:27]
	v_mfma_f32_16x16x32_bf16 v[12:15], v[152:155], v[244:247], v[12:15]
	v_mfma_f32_16x16x32_bf16 v[8:11], v[160:163], v[244:247], v[8:11]
	v_mfma_f32_16x16x32_bf16 v[52:55], v[164:167], v[188:191], 0
	v_mfma_f32_16x16x32_bf16 v[48:51], v[172:175], v[188:191], 0
	v_mfma_f32_16x16x32_bf16 v[36:39], v[164:167], v[224:227], 0
	v_mfma_f32_16x16x32_bf16 v[32:35], v[172:175], v[224:227], 0
	v_mfma_f32_16x16x32_bf16 v[20:23], v[164:167], v[232:235], 0
	v_mfma_f32_16x16x32_bf16 v[16:19], v[172:175], v[232:235], 0
	v_mfma_f32_16x16x32_bf16 v[4:7], v[164:167], v[240:243], 0
	v_mfma_f32_16x16x32_bf16 v[0:3], v[172:175], v[240:243], 0
	v_mfma_f32_16x16x32_bf16 v[52:55], v[168:171], v[220:223], v[52:55]
	v_mfma_f32_16x16x32_bf16 v[48:51], v[176:179], v[220:223], v[48:51]
	v_mfma_f32_16x16x32_bf16 v[36:39], v[168:171], v[228:231], v[36:39]
	v_mfma_f32_16x16x32_bf16 v[32:35], v[176:179], v[228:231], v[32:35]
	v_mfma_f32_16x16x32_bf16 v[20:23], v[168:171], v[236:239], v[20:23]
	v_mfma_f32_16x16x32_bf16 v[16:19], v[176:179], v[236:239], v[16:19]
	v_mfma_f32_16x16x32_bf16 v[4:7], v[168:171], v[244:247], v[4:7]
	v_mfma_f32_16x16x32_bf16 v[0:3], v[176:179], v[244:247], v[0:3]
	s_barrier
	s_setprio 0
	v_add_u32_e32 v160, 0x18000, v145
	v_add_u32_e32 v176, 0x1c000, v145
	ds_read_b128 v[140:143], v160
	ds_read_b128 v[152:155], v160 offset:1024
	ds_read_b128 v[156:159], v160 offset:2048
	ds_read_b128 v[160:163], v160 offset:3072
	ds_read_b128 v[164:167], v176
	ds_read_b128 v[168:171], v176 offset:1024
	ds_read_b128 v[172:175], v176 offset:2048
	ds_read_b128 v[176:179], v176 offset:3072
	s_add_i32 s0, 0, 0x18000
	s_add_i32 s96, 0, 0x1c000
	s_add_u32 s88, s88, 0x40000
	s_addc_u32 s89, s89, 0
	s_mov_b32 m0, s26
	v_lshl_add_u64 v[252:253], s[88:89], 0, v[96:97]
	ds_read_b128 v[188:191], v151 offset:32768
	ds_read_b128 v[220:223], v151 offset:33792
	ds_read_b128 v[224:227], v151 offset:34816
	ds_read_b128 v[228:231], v151 offset:35840
	ds_read_b128 v[232:235], v151 offset:36864
	ds_read_b128 v[236:239], v151 offset:37888
	ds_read_b128 v[240:243], v151 offset:38912
	ds_read_b128 v[244:247], v151 offset:39936
	global_load_lds_dwordx4 v[252:253], off
	v_lshl_add_u64 v[252:253], s[88:89], 0, v[132:133]
	s_mov_b32 m0, s27
	s_nop 0
	global_load_lds_dwordx4 v[252:253], off
	s_waitcnt vmcnt(8)
	s_waitcnt lgkmcnt(0)
	s_setprio 1
	s_barrier
	v_mfma_f32_16x16x32_bf16 v[128:131], v[140:143], v[188:191], v[128:131]
	v_mfma_f32_16x16x32_bf16 v[124:127], v[156:159], v[188:191], v[124:127]
	v_mfma_f32_16x16x32_bf16 v[112:115], v[140:143], v[224:227], v[112:115]
	v_mfma_f32_16x16x32_bf16 v[108:111], v[156:159], v[224:227], v[108:111]
	v_mfma_f32_16x16x32_bf16 v[92:95], v[140:143], v[232:235], v[92:95]
	v_mfma_f32_16x16x32_bf16 v[88:91], v[156:159], v[232:235], v[88:91]
	v_mfma_f32_16x16x32_bf16 v[76:79], v[140:143], v[240:243], v[76:79]
	v_mfma_f32_16x16x32_bf16 v[72:75], v[156:159], v[240:243], v[72:75]
	v_mfma_f32_16x16x32_bf16 v[128:131], v[152:155], v[220:223], v[128:131]
	v_mfma_f32_16x16x32_bf16 v[124:127], v[160:163], v[220:223], v[124:127]
	v_mfma_f32_16x16x32_bf16 v[112:115], v[152:155], v[228:231], v[112:115]
	v_mfma_f32_16x16x32_bf16 v[108:111], v[160:163], v[228:231], v[108:111]
	v_mfma_f32_16x16x32_bf16 v[92:95], v[152:155], v[236:239], v[92:95]
	v_mfma_f32_16x16x32_bf16 v[88:91], v[160:163], v[236:239], v[88:91]
	v_mfma_f32_16x16x32_bf16 v[76:79], v[152:155], v[244:247], v[76:79]
	v_mfma_f32_16x16x32_bf16 v[72:75], v[160:163], v[244:247], v[72:75]
	v_mfma_f32_16x16x32_bf16 v[120:123], v[164:167], v[188:191], v[120:123]
	v_mfma_f32_16x16x32_bf16 v[116:119], v[172:175], v[188:191], v[116:119]
	v_mfma_f32_16x16x32_bf16 v[104:107], v[164:167], v[224:227], v[104:107]
	v_mfma_f32_16x16x32_bf16 v[100:103], v[172:175], v[224:227], v[100:103]
	v_mfma_f32_16x16x32_bf16 v[84:87], v[164:167], v[232:235], v[84:87]
	v_mfma_f32_16x16x32_bf16 v[80:83], v[172:175], v[232:235], v[80:83]
	v_mfma_f32_16x16x32_bf16 v[68:71], v[164:167], v[240:243], v[68:71]
	v_mfma_f32_16x16x32_bf16 v[64:67], v[172:175], v[240:243], v[64:67]
	v_mfma_f32_16x16x32_bf16 v[120:123], v[168:171], v[220:223], v[120:123]
	v_mfma_f32_16x16x32_bf16 v[116:119], v[176:179], v[220:223], v[116:119]
	v_mfma_f32_16x16x32_bf16 v[104:107], v[168:171], v[228:231], v[104:107]
	v_mfma_f32_16x16x32_bf16 v[100:103], v[176:179], v[228:231], v[100:103]
	v_mfma_f32_16x16x32_bf16 v[84:87], v[168:171], v[236:239], v[84:87]
	v_mfma_f32_16x16x32_bf16 v[80:83], v[176:179], v[236:239], v[80:83]
	v_mfma_f32_16x16x32_bf16 v[68:71], v[168:171], v[244:247], v[68:71]
	v_mfma_f32_16x16x32_bf16 v[64:67], v[176:179], v[244:247], v[64:67]
	s_barrier
	s_setprio 0
	ds_read_b128 v[188:191], v151 offset:49152
	ds_read_b128 v[220:223], v151 offset:50176
	ds_read_b128 v[224:227], v151 offset:51200
	ds_read_b128 v[228:231], v151 offset:52224
	ds_read_b128 v[232:235], v151 offset:53248
	ds_read_b128 v[236:239], v151 offset:54272
	ds_read_b128 v[240:243], v151 offset:55296
	ds_read_b128 v[244:247], v151 offset:56320
	s_add_i32 s0, s0, s1
	s_mov_b32 m0, s0
	v_lshl_add_u64 v[180:181], v[180:181], 0, s[58:59]
	global_load_lds_dwordx4 v[180:181], off
	s_add_i32 m0, s0, 0x2000
	s_add_u32 s86, s86, 0x40080
	v_lshl_add_u64 v[180:181], v[192:193], 0, s[58:59]
	s_addc_u32 s87, s87, 0
	s_add_i32 s0, s96, s1
	global_load_lds_dwordx4 v[180:181], off
	v_lshl_add_u64 v[180:181], s[86:87], 0, v[98:99]
	s_mov_b32 m0, s0
	s_nop 0
	global_load_lds_dwordx4 v[180:181], off
	v_lshl_add_u64 v[180:181], s[86:87], 0, v[134:135]
	s_add_i32 m0, s0, 0x2000
	s_nop 0
	global_load_lds_dwordx4 v[180:181], off
	v_lshl_add_u64 v[180:181], v[248:249], 0, s[58:59]
	s_mov_b32 m0, s42
	s_nop 0
	global_load_lds_dwordx4 v[180:181], off
	v_lshl_add_u64 v[180:181], v[250:251], 0, s[58:59]
	s_mov_b32 m0, s43
	s_nop 0
	global_load_lds_dwordx4 v[180:181], off
	s_waitcnt vmcnt(8)
	s_waitcnt lgkmcnt(0)
	s_setprio 1
	s_barrier
	v_mfma_f32_16x16x32_bf16 v[60:63], v[140:143], v[188:191], v[60:63]
	v_mfma_f32_16x16x32_bf16 v[56:59], v[156:159], v[188:191], v[56:59]
	v_mfma_f32_16x16x32_bf16 v[44:47], v[140:143], v[224:227], v[44:47]
	v_mfma_f32_16x16x32_bf16 v[40:43], v[156:159], v[224:227], v[40:43]
	v_mfma_f32_16x16x32_bf16 v[28:31], v[140:143], v[232:235], v[28:31]
	v_mfma_f32_16x16x32_bf16 v[24:27], v[156:159], v[232:235], v[24:27]
	v_mfma_f32_16x16x32_bf16 v[12:15], v[140:143], v[240:243], v[12:15]
	v_mfma_f32_16x16x32_bf16 v[8:11], v[156:159], v[240:243], v[8:11]
	v_mfma_f32_16x16x32_bf16 v[60:63], v[152:155], v[220:223], v[60:63]
	v_mfma_f32_16x16x32_bf16 v[56:59], v[160:163], v[220:223], v[56:59]
	v_mfma_f32_16x16x32_bf16 v[44:47], v[152:155], v[228:231], v[44:47]
	v_mfma_f32_16x16x32_bf16 v[40:43], v[160:163], v[228:231], v[40:43]
	v_mfma_f32_16x16x32_bf16 v[28:31], v[152:155], v[236:239], v[28:31]
	v_mfma_f32_16x16x32_bf16 v[24:27], v[160:163], v[236:239], v[24:27]
	v_mfma_f32_16x16x32_bf16 v[12:15], v[152:155], v[244:247], v[12:15]
	v_mfma_f32_16x16x32_bf16 v[8:11], v[160:163], v[244:247], v[8:11]
	v_mfma_f32_16x16x32_bf16 v[52:55], v[164:167], v[188:191], v[52:55]
	v_mfma_f32_16x16x32_bf16 v[48:51], v[172:175], v[188:191], v[48:51]
	v_mfma_f32_16x16x32_bf16 v[36:39], v[164:167], v[224:227], v[36:39]
	v_mfma_f32_16x16x32_bf16 v[32:35], v[172:175], v[224:227], v[32:35]
	v_mfma_f32_16x16x32_bf16 v[20:23], v[164:167], v[232:235], v[20:23]
	v_mfma_f32_16x16x32_bf16 v[16:19], v[172:175], v[232:235], v[16:19]
	v_mfma_f32_16x16x32_bf16 v[4:7], v[164:167], v[240:243], v[4:7]
	v_mfma_f32_16x16x32_bf16 v[0:3], v[172:175], v[240:243], v[0:3]
	v_mfma_f32_16x16x32_bf16 v[52:55], v[168:171], v[220:223], v[52:55]
	v_mfma_f32_16x16x32_bf16 v[48:51], v[176:179], v[220:223], v[48:51]
	v_mfma_f32_16x16x32_bf16 v[36:39], v[168:171], v[228:231], v[36:39]
	v_mfma_f32_16x16x32_bf16 v[32:35], v[176:179], v[228:231], v[32:35]
	v_mfma_f32_16x16x32_bf16 v[20:23], v[168:171], v[236:239], v[20:23]
	v_mfma_f32_16x16x32_bf16 v[16:19], v[176:179], v[236:239], v[16:19]
	v_mfma_f32_16x16x32_bf16 v[4:7], v[168:171], v[244:247], v[4:7]
	v_mfma_f32_16x16x32_bf16 v[0:3], v[176:179], v[244:247], v[0:3]
	s_barrier
	s_setprio 0
	s_cmp_gt_u32 s90, 13
	s_cbranch_scc1 .Lpeel_exit_232
.LBB0_232:
	v_add_u32_e32 v160, 0x10000, v145
	v_add_u32_e32 v176, 0x14000, v145
	ds_read_b128 v[140:143], v160
	ds_read_b128 v[152:155], v160 offset:1024
	ds_read_b128 v[156:159], v160 offset:2048
	ds_read_b128 v[160:163], v160 offset:3072
	ds_read_b128 v[164:167], v176
	ds_read_b128 v[168:171], v176 offset:1024
	ds_read_b128 v[172:175], v176 offset:2048
	ds_read_b128 v[176:179], v176 offset:3072
	s_add_u32 s0, s84, 0xfffc0080
	s_addc_u32 s86, s85, -1
	s_add_i32 s96, 0, 0x10000
	s_cmp_eq_u32 s90, 12
	s_cselect_b32 s89, s66, s86
	s_cselect_b32 s88, s67, s0
	s_cselect_b32 s87, s68, s77
	s_cselect_b32 s86, s69, s75
	s_add_i32 s0, 0, 0x14000
	v_lshl_add_u64 v[180:181], s[84:85], 0, v[136:137]
	s_add_i32 m0, s22, 0xc000
	ds_read_b128 v[188:191], v151
	ds_read_b128 v[220:223], v151 offset:1024
	ds_read_b128 v[224:227], v151 offset:2048
	ds_read_b128 v[228:231], v151 offset:3072
	ds_read_b128 v[232:235], v151 offset:4096
	ds_read_b128 v[236:239], v151 offset:5120
	ds_read_b128 v[240:243], v151 offset:6144
	ds_read_b128 v[244:247], v151 offset:7168
	global_load_lds_dwordx4 v[180:181], off
	v_lshl_add_u64 v[180:181], s[84:85], 0, v[138:139]
	s_add_i32 m0, s22, 0xe000
	s_nop 0
	global_load_lds_dwordx4 v[180:181], off
	s_waitcnt vmcnt(8)
	s_waitcnt lgkmcnt(0)
	s_setprio 1
	s_barrier
	v_mfma_f32_16x16x32_bf16 v[128:131], v[140:143], v[188:191], v[128:131]
	v_mfma_f32_16x16x32_bf16 v[124:127], v[156:159], v[188:191], v[124:127]
	v_mfma_f32_16x16x32_bf16 v[112:115], v[140:143], v[224:227], v[112:115]
	v_mfma_f32_16x16x32_bf16 v[108:111], v[156:159], v[224:227], v[108:111]
	v_mfma_f32_16x16x32_bf16 v[92:95], v[140:143], v[232:235], v[92:95]
	v_mfma_f32_16x16x32_bf16 v[88:91], v[156:159], v[232:235], v[88:91]
	v_mfma_f32_16x16x32_bf16 v[76:79], v[140:143], v[240:243], v[76:79]
	v_mfma_f32_16x16x32_bf16 v[72:75], v[156:159], v[240:243], v[72:75]
	v_mfma_f32_16x16x32_bf16 v[128:131], v[152:155], v[220:223], v[128:131]
	v_mfma_f32_16x16x32_bf16 v[124:127], v[160:163], v[220:223], v[124:127]
	v_mfma_f32_16x16x32_bf16 v[112:115], v[152:155], v[228:231], v[112:115]
	v_mfma_f32_16x16x32_bf16 v[108:111], v[160:163], v[228:231], v[108:111]
	v_mfma_f32_16x16x32_bf16 v[92:95], v[152:155], v[236:239], v[92:95]
	v_mfma_f32_16x16x32_bf16 v[88:91], v[160:163], v[236:239], v[88:91]
	v_mfma_f32_16x16x32_bf16 v[76:79], v[152:155], v[244:247], v[76:79]
	v_mfma_f32_16x16x32_bf16 v[72:75], v[160:163], v[244:247], v[72:75]
	v_mfma_f32_16x16x32_bf16 v[120:123], v[164:167], v[188:191], v[120:123]
	v_mfma_f32_16x16x32_bf16 v[116:119], v[172:175], v[188:191], v[116:119]
	v_mfma_f32_16x16x32_bf16 v[104:107], v[164:167], v[224:227], v[104:107]
	v_mfma_f32_16x16x32_bf16 v[100:103], v[172:175], v[224:227], v[100:103]
	v_mfma_f32_16x16x32_bf16 v[84:87], v[164:167], v[232:235], v[84:87]
	v_mfma_f32_16x16x32_bf16 v[80:83], v[172:175], v[232:235], v[80:83]
	v_mfma_f32_16x16x32_bf16 v[68:71], v[164:167], v[240:243], v[68:71]
	v_mfma_f32_16x16x32_bf16 v[64:67], v[172:175], v[240:243], v[64:67]
	v_mfma_f32_16x16x32_bf16 v[120:123], v[168:171], v[220:223], v[120:123]
	v_mfma_f32_16x16x32_bf16 v[116:119], v[176:179], v[220:223], v[116:119]
	v_mfma_f32_16x16x32_bf16 v[104:107], v[168:171], v[228:231], v[104:107]
	v_mfma_f32_16x16x32_bf16 v[100:103], v[176:179], v[228:231], v[100:103]
	v_mfma_f32_16x16x32_bf16 v[84:87], v[168:171], v[236:239], v[84:87]
	v_mfma_f32_16x16x32_bf16 v[80:83], v[176:179], v[236:239], v[80:83]
	v_mfma_f32_16x16x32_bf16 v[68:71], v[168:171], v[244:247], v[68:71]
	v_mfma_f32_16x16x32_bf16 v[64:67], v[176:179], v[244:247], v[64:67]
	s_barrier
	s_setprio 0
	ds_read_b128 v[188:191], v151 offset:16384
	ds_read_b128 v[220:223], v151 offset:17408
	ds_read_b128 v[224:227], v151 offset:18432
	ds_read_b128 v[228:231], v151 offset:19456
	ds_read_b128 v[232:235], v151 offset:20480
	ds_read_b128 v[236:239], v151 offset:21504
	ds_read_b128 v[240:243], v151 offset:22528
	ds_read_b128 v[244:247], v151 offset:23552
	s_add_i32 s90, s90, 2
	s_add_u32 s84, s84, 0x100
	s_addc_u32 s85, s85, 0
	s_add_u32 s75, s75, 0x100
	s_addc_u32 s77, s77, 0
	s_add_i32 s96, s96, s1
	s_mov_b32 m0, s96
	v_lshl_add_u64 v[180:181], s[86:87], 0, v[98:99]
	global_load_lds_dwordx4 v[180:181], off
	s_add_i32 m0, s96, 0x2000
	s_add_u32 s96, s86, 0x40000
	v_lshl_add_u64 v[192:193], s[86:87], 0, v[134:135]
	s_addc_u32 s97, s87, 0
	s_add_i32 s0, s0, s1
	global_load_lds_dwordx4 v[192:193], off
	v_lshl_add_u64 v[248:249], s[96:97], 0, v[98:99]
	s_mov_b32 m0, s0
	v_lshl_add_u64 v[250:251], s[88:89], 0, v[132:133]
	global_load_lds_dwordx4 v[248:249], off
	v_lshl_add_u64 v[248:249], s[96:97], 0, v[134:135]
	s_add_i32 m0, s0, 0x2000
	s_nop 0
	global_load_lds_dwordx4 v[248:249], off
	v_lshl_add_u64 v[248:249], s[88:89], 0, v[96:97]
	s_mov_b32 m0, s22
	s_nop 0
	global_load_lds_dwordx4 v[248:249], off
	s_mov_b32 m0, s23
	s_nop 0
	global_load_lds_dwordx4 v[250:251], off
	s_waitcnt vmcnt(8)
	s_waitcnt lgkmcnt(0)
	s_setprio 1
	s_barrier
	v_mfma_f32_16x16x32_bf16 v[60:63], v[140:143], v[188:191], v[60:63]
	v_mfma_f32_16x16x32_bf16 v[56:59], v[156:159], v[188:191], v[56:59]
	v_mfma_f32_16x16x32_bf16 v[44:47], v[140:143], v[224:227], v[44:47]
	v_mfma_f32_16x16x32_bf16 v[40:43], v[156:159], v[224:227], v[40:43]
	v_mfma_f32_16x16x32_bf16 v[28:31], v[140:143], v[232:235], v[28:31]
	v_mfma_f32_16x16x32_bf16 v[24:27], v[156:159], v[232:235], v[24:27]
	v_mfma_f32_16x16x32_bf16 v[12:15], v[140:143], v[240:243], v[12:15]
	v_mfma_f32_16x16x32_bf16 v[8:11], v[156:159], v[240:243], v[8:11]
	v_mfma_f32_16x16x32_bf16 v[60:63], v[152:155], v[220:223], v[60:63]
	v_mfma_f32_16x16x32_bf16 v[56:59], v[160:163], v[220:223], v[56:59]
	v_mfma_f32_16x16x32_bf16 v[44:47], v[152:155], v[228:231], v[44:47]
	v_mfma_f32_16x16x32_bf16 v[40:43], v[160:163], v[228:231], v[40:43]
	v_mfma_f32_16x16x32_bf16 v[28:31], v[152:155], v[236:239], v[28:31]
	v_mfma_f32_16x16x32_bf16 v[24:27], v[160:163], v[236:239], v[24:27]
	v_mfma_f32_16x16x32_bf16 v[12:15], v[152:155], v[244:247], v[12:15]
	v_mfma_f32_16x16x32_bf16 v[8:11], v[160:163], v[244:247], v[8:11]
	v_mfma_f32_16x16x32_bf16 v[52:55], v[164:167], v[188:191], v[52:55]
	v_mfma_f32_16x16x32_bf16 v[48:51], v[172:175], v[188:191], v[48:51]
	v_mfma_f32_16x16x32_bf16 v[36:39], v[164:167], v[224:227], v[36:39]
	v_mfma_f32_16x16x32_bf16 v[32:35], v[172:175], v[224:227], v[32:35]
	v_mfma_f32_16x16x32_bf16 v[20:23], v[164:167], v[232:235], v[20:23]
	v_mfma_f32_16x16x32_bf16 v[16:19], v[172:175], v[232:235], v[16:19]
	v_mfma_f32_16x16x32_bf16 v[4:7], v[164:167], v[240:243], v[4:7]
	v_mfma_f32_16x16x32_bf16 v[0:3], v[172:175], v[240:243], v[0:3]
	v_mfma_f32_16x16x32_bf16 v[52:55], v[168:171], v[220:223], v[52:55]
	v_mfma_f32_16x16x32_bf16 v[48:51], v[176:179], v[220:223], v[48:51]
	v_mfma_f32_16x16x32_bf16 v[36:39], v[168:171], v[228:231], v[36:39]
	v_mfma_f32_16x16x32_bf16 v[32:35], v[176:179], v[228:231], v[32:35]
	v_mfma_f32_16x16x32_bf16 v[20:23], v[168:171], v[236:239], v[20:23]
	v_mfma_f32_16x16x32_bf16 v[16:19], v[176:179], v[236:239], v[16:19]
	v_mfma_f32_16x16x32_bf16 v[4:7], v[168:171], v[244:247], v[4:7]
	v_mfma_f32_16x16x32_bf16 v[0:3], v[176:179], v[244:247], v[0:3]
	s_barrier
	s_setprio 0
	v_add_u32_e32 v160, 0x18000, v145
	v_add_u32_e32 v176, 0x1c000, v145
	ds_read_b128 v[140:143], v160
	ds_read_b128 v[152:155], v160 offset:1024
	ds_read_b128 v[156:159], v160 offset:2048
	ds_read_b128 v[160:163], v160 offset:3072
	ds_read_b128 v[164:167], v176
	ds_read_b128 v[168:171], v176 offset:1024
	ds_read_b128 v[172:175], v176 offset:2048
	ds_read_b128 v[176:179], v176 offset:3072
	s_add_i32 s0, 0, 0x18000
	s_add_i32 s96, 0, 0x1c000
	s_add_u32 s88, s88, 0x40000
	s_addc_u32 s89, s89, 0
	s_mov_b32 m0, s26
	v_lshl_add_u64 v[252:253], s[88:89], 0, v[96:97]
	ds_read_b128 v[188:191], v151 offset:32768
	ds_read_b128 v[220:223], v151 offset:33792
	ds_read_b128 v[224:227], v151 offset:34816
	ds_read_b128 v[228:231], v151 offset:35840
	ds_read_b128 v[232:235], v151 offset:36864
	ds_read_b128 v[236:239], v151 offset:37888
	ds_read_b128 v[240:243], v151 offset:38912
	ds_read_b128 v[244:247], v151 offset:39936
	global_load_lds_dwordx4 v[252:253], off
	v_lshl_add_u64 v[252:253], s[88:89], 0, v[132:133]
	s_mov_b32 m0, s27
	s_nop 0
	global_load_lds_dwordx4 v[252:253], off
	s_waitcnt vmcnt(8)
	s_waitcnt lgkmcnt(0)
	s_setprio 1
	s_barrier
	v_mfma_f32_16x16x32_bf16 v[128:131], v[140:143], v[188:191], v[128:131]
	v_mfma_f32_16x16x32_bf16 v[124:127], v[156:159], v[188:191], v[124:127]
	v_mfma_f32_16x16x32_bf16 v[112:115], v[140:143], v[224:227], v[112:115]
	v_mfma_f32_16x16x32_bf16 v[108:111], v[156:159], v[224:227], v[108:111]
	v_mfma_f32_16x16x32_bf16 v[92:95], v[140:143], v[232:235], v[92:95]
	v_mfma_f32_16x16x32_bf16 v[88:91], v[156:159], v[232:235], v[88:91]
	v_mfma_f32_16x16x32_bf16 v[76:79], v[140:143], v[240:243], v[76:79]
	v_mfma_f32_16x16x32_bf16 v[72:75], v[156:159], v[240:243], v[72:75]
	v_mfma_f32_16x16x32_bf16 v[128:131], v[152:155], v[220:223], v[128:131]
	v_mfma_f32_16x16x32_bf16 v[124:127], v[160:163], v[220:223], v[124:127]
	v_mfma_f32_16x16x32_bf16 v[112:115], v[152:155], v[228:231], v[112:115]
	v_mfma_f32_16x16x32_bf16 v[108:111], v[160:163], v[228:231], v[108:111]
	v_mfma_f32_16x16x32_bf16 v[92:95], v[152:155], v[236:239], v[92:95]
	v_mfma_f32_16x16x32_bf16 v[88:91], v[160:163], v[236:239], v[88:91]
	v_mfma_f32_16x16x32_bf16 v[76:79], v[152:155], v[244:247], v[76:79]
	v_mfma_f32_16x16x32_bf16 v[72:75], v[160:163], v[244:247], v[72:75]
	v_mfma_f32_16x16x32_bf16 v[120:123], v[164:167], v[188:191], v[120:123]
	v_mfma_f32_16x16x32_bf16 v[116:119], v[172:175], v[188:191], v[116:119]
	v_mfma_f32_16x16x32_bf16 v[104:107], v[164:167], v[224:227], v[104:107]
	v_mfma_f32_16x16x32_bf16 v[100:103], v[172:175], v[224:227], v[100:103]
	v_mfma_f32_16x16x32_bf16 v[84:87], v[164:167], v[232:235], v[84:87]
	v_mfma_f32_16x16x32_bf16 v[80:83], v[172:175], v[232:235], v[80:83]
	v_mfma_f32_16x16x32_bf16 v[68:71], v[164:167], v[240:243], v[68:71]
	v_mfma_f32_16x16x32_bf16 v[64:67], v[172:175], v[240:243], v[64:67]
	v_mfma_f32_16x16x32_bf16 v[120:123], v[168:171], v[220:223], v[120:123]
	v_mfma_f32_16x16x32_bf16 v[116:119], v[176:179], v[220:223], v[116:119]
	v_mfma_f32_16x16x32_bf16 v[104:107], v[168:171], v[228:231], v[104:107]
	v_mfma_f32_16x16x32_bf16 v[100:103], v[176:179], v[228:231], v[100:103]
	v_mfma_f32_16x16x32_bf16 v[84:87], v[168:171], v[236:239], v[84:87]
	v_mfma_f32_16x16x32_bf16 v[80:83], v[176:179], v[236:239], v[80:83]
	v_mfma_f32_16x16x32_bf16 v[68:71], v[168:171], v[244:247], v[68:71]
	v_mfma_f32_16x16x32_bf16 v[64:67], v[176:179], v[244:247], v[64:67]
	s_barrier
	s_setprio 0
	ds_read_b128 v[188:191], v151 offset:49152
	ds_read_b128 v[220:223], v151 offset:50176
	ds_read_b128 v[224:227], v151 offset:51200
	ds_read_b128 v[228:231], v151 offset:52224
	ds_read_b128 v[232:235], v151 offset:53248
	ds_read_b128 v[236:239], v151 offset:54272
	ds_read_b128 v[240:243], v151 offset:55296
	ds_read_b128 v[244:247], v151 offset:56320
	s_add_i32 s0, s0, s1
	s_mov_b32 m0, s0
	v_lshl_add_u64 v[180:181], v[180:181], 0, s[58:59]
	global_load_lds_dwordx4 v[180:181], off
	s_add_i32 m0, s0, 0x2000
	s_add_u32 s86, s86, 0x40080
	v_lshl_add_u64 v[180:181], v[192:193], 0, s[58:59]
	s_addc_u32 s87, s87, 0
	s_add_i32 s0, s96, s1
	global_load_lds_dwordx4 v[180:181], off
	v_lshl_add_u64 v[180:181], s[86:87], 0, v[98:99]
	s_mov_b32 m0, s0
	s_nop 0
	global_load_lds_dwordx4 v[180:181], off
	v_lshl_add_u64 v[180:181], s[86:87], 0, v[134:135]
	s_add_i32 m0, s0, 0x2000
	s_nop 0
	global_load_lds_dwordx4 v[180:181], off
	v_lshl_add_u64 v[180:181], v[248:249], 0, s[58:59]
	s_mov_b32 m0, s42
	s_nop 0
	global_load_lds_dwordx4 v[180:181], off
	v_lshl_add_u64 v[180:181], v[250:251], 0, s[58:59]
	s_mov_b32 m0, s43
	s_nop 0
	global_load_lds_dwordx4 v[180:181], off
	s_waitcnt vmcnt(8)
	s_waitcnt lgkmcnt(0)
	s_setprio 1
	s_barrier
	v_mfma_f32_16x16x32_bf16 v[60:63], v[140:143], v[188:191], v[60:63]
	v_mfma_f32_16x16x32_bf16 v[56:59], v[156:159], v[188:191], v[56:59]
	v_mfma_f32_16x16x32_bf16 v[44:47], v[140:143], v[224:227], v[44:47]
	v_mfma_f32_16x16x32_bf16 v[40:43], v[156:159], v[224:227], v[40:43]
	v_mfma_f32_16x16x32_bf16 v[28:31], v[140:143], v[232:235], v[28:31]
	v_mfma_f32_16x16x32_bf16 v[24:27], v[156:159], v[232:235], v[24:27]
	v_mfma_f32_16x16x32_bf16 v[12:15], v[140:143], v[240:243], v[12:15]
	v_mfma_f32_16x16x32_bf16 v[8:11], v[156:159], v[240:243], v[8:11]
	v_mfma_f32_16x16x32_bf16 v[60:63], v[152:155], v[220:223], v[60:63]
	v_mfma_f32_16x16x32_bf16 v[56:59], v[160:163], v[220:223], v[56:59]
	v_mfma_f32_16x16x32_bf16 v[44:47], v[152:155], v[228:231], v[44:47]
	v_mfma_f32_16x16x32_bf16 v[40:43], v[160:163], v[228:231], v[40:43]
	v_mfma_f32_16x16x32_bf16 v[28:31], v[152:155], v[236:239], v[28:31]
	v_mfma_f32_16x16x32_bf16 v[24:27], v[160:163], v[236:239], v[24:27]
	v_mfma_f32_16x16x32_bf16 v[12:15], v[152:155], v[244:247], v[12:15]
	v_mfma_f32_16x16x32_bf16 v[8:11], v[160:163], v[244:247], v[8:11]
	v_mfma_f32_16x16x32_bf16 v[52:55], v[164:167], v[188:191], v[52:55]
	v_mfma_f32_16x16x32_bf16 v[48:51], v[172:175], v[188:191], v[48:51]
	v_mfma_f32_16x16x32_bf16 v[36:39], v[164:167], v[224:227], v[36:39]
	v_mfma_f32_16x16x32_bf16 v[32:35], v[172:175], v[224:227], v[32:35]
	v_mfma_f32_16x16x32_bf16 v[20:23], v[164:167], v[232:235], v[20:23]
	v_mfma_f32_16x16x32_bf16 v[16:19], v[172:175], v[232:235], v[16:19]
	v_mfma_f32_16x16x32_bf16 v[4:7], v[164:167], v[240:243], v[4:7]
	v_mfma_f32_16x16x32_bf16 v[0:3], v[172:175], v[240:243], v[0:3]
	v_mfma_f32_16x16x32_bf16 v[52:55], v[168:171], v[220:223], v[52:55]
	v_mfma_f32_16x16x32_bf16 v[48:51], v[176:179], v[220:223], v[48:51]
	v_mfma_f32_16x16x32_bf16 v[36:39], v[168:171], v[228:231], v[36:39]
	v_mfma_f32_16x16x32_bf16 v[32:35], v[176:179], v[228:231], v[32:35]
	v_mfma_f32_16x16x32_bf16 v[20:23], v[168:171], v[236:239], v[20:23]
	v_mfma_f32_16x16x32_bf16 v[16:19], v[176:179], v[236:239], v[16:19]
	v_mfma_f32_16x16x32_bf16 v[4:7], v[168:171], v[244:247], v[4:7]
	v_mfma_f32_16x16x32_bf16 v[0:3], v[176:179], v[244:247], v[0:3]
	s_barrier
	s_setprio 0
	s_cmp_gt_u32 s90, 13
	s_cbranch_scc0 .LBB0_232

.LBB0_309:
	s_add_u32 s84, s84, 0x80
	s_addc_u32 s85, s85, 0
	s_add_u32 s26, s86, 0x100
	s_addc_u32 s27, s87, 0
	s_mov_b32 s0, 0
	s_waitcnt lgkmcnt(0)
	s_waitcnt vmcnt(0)
	v_add_u32_e32 v152, 0x10000, v161
	v_add_u32_e32 v172, 0x14000, v161
	ds_read_b128 v[132:135], v152
	ds_read_b128 v[136:139], v152 offset:1024
	ds_read_b128 v[148:151], v152 offset:2048
	ds_read_b128 v[152:155], v152 offset:3072
	ds_read_b128 v[156:159], v172
	ds_read_b128 v[164:167], v172 offset:1024
	ds_read_b128 v[168:171], v172 offset:2048
	ds_read_b128 v[172:175], v172 offset:3072
	s_add_i32 s42, s0, 2
	s_add_u32 s66, s84, 0x80
	s_addc_u32 s86, s85, 0
	s_add_i32 s97, 0, 0x10000
	s_cmp_eq_u32 s88, s0
	s_cselect_b32 s87, s81, s86
	s_cselect_b32 s86, s80, s66
	s_cselect_b32 vcc_hi, s83, s27
	s_cselect_b32 vcc_lo, s82, s26
	s_add_i32 s0, 0, 0x14000
	v_lshl_add_u64 v[180:181], s[84:85], 0, v[144:145]
	s_add_i32 m0, s23, 0xc000
	ds_read_b128 v[176:179], v163
	ds_read_b128 v[188:191], v163 offset:1024
	ds_read_b128 v[220:223], v163 offset:2048
	ds_read_b128 v[224:227], v163 offset:3072
	ds_read_b128 v[228:231], v163 offset:4096
	ds_read_b128 v[232:235], v163 offset:5120
	ds_read_b128 v[236:239], v163 offset:6144
	ds_read_b128 v[240:243], v163 offset:7168
	global_load_lds_dwordx4 v[180:181], off
	v_lshl_add_u64 v[180:181], s[84:85], 0, v[146:147]
	s_add_i32 m0, s23, 0xe000
	s_nop 0
	global_load_lds_dwordx4 v[180:181], off
	s_waitcnt vmcnt(8)
	s_waitcnt lgkmcnt(0)
	s_setprio 1
	s_barrier
	v_mfma_f32_16x16x32_bf16 v[128:131], v[132:135], v[176:179], 0
	v_mfma_f32_16x16x32_bf16 v[124:127], v[148:151], v[176:179], 0
	v_mfma_f32_16x16x32_bf16 v[112:115], v[132:135], v[220:223], 0
	v_mfma_f32_16x16x32_bf16 v[108:111], v[148:151], v[220:223], 0
	v_mfma_f32_16x16x32_bf16 v[92:95], v[132:135], v[228:231], 0
	v_mfma_f32_16x16x32_bf16 v[88:91], v[148:151], v[228:231], 0
	v_mfma_f32_16x16x32_bf16 v[76:79], v[132:135], v[236:239], 0
	v_mfma_f32_16x16x32_bf16 v[72:75], v[148:151], v[236:239], 0
	v_mfma_f32_16x16x32_bf16 v[128:131], v[136:139], v[188:191], v[128:131]
	v_mfma_f32_16x16x32_bf16 v[124:127], v[152:155], v[188:191], v[124:127]
	v_mfma_f32_16x16x32_bf16 v[112:115], v[136:139], v[224:227], v[112:115]
	v_mfma_f32_16x16x32_bf16 v[108:111], v[152:155], v[224:227], v[108:111]
	v_mfma_f32_16x16x32_bf16 v[92:95], v[136:139], v[232:235], v[92:95]
	v_mfma_f32_16x16x32_bf16 v[88:91], v[152:155], v[232:235], v[88:91]
	v_mfma_f32_16x16x32_bf16 v[76:79], v[136:139], v[240:243], v[76:79]
	v_mfma_f32_16x16x32_bf16 v[72:75], v[152:155], v[240:243], v[72:75]
	v_mfma_f32_16x16x32_bf16 v[120:123], v[156:159], v[176:179], 0
	v_mfma_f32_16x16x32_bf16 v[116:119], v[168:171], v[176:179], 0
	v_mfma_f32_16x16x32_bf16 v[104:107], v[156:159], v[220:223], 0
	v_mfma_f32_16x16x32_bf16 v[100:103], v[168:171], v[220:223], 0
	v_mfma_f32_16x16x32_bf16 v[84:87], v[156:159], v[228:231], 0
	v_mfma_f32_16x16x32_bf16 v[80:83], v[168:171], v[228:231], 0
	v_mfma_f32_16x16x32_bf16 v[68:71], v[156:159], v[236:239], 0
	v_mfma_f32_16x16x32_bf16 v[64:67], v[168:171], v[236:239], 0
	v_mfma_f32_16x16x32_bf16 v[120:123], v[164:167], v[188:191], v[120:123]
	v_mfma_f32_16x16x32_bf16 v[116:119], v[172:175], v[188:191], v[116:119]
	v_mfma_f32_16x16x32_bf16 v[104:107], v[164:167], v[224:227], v[104:107]
	v_mfma_f32_16x16x32_bf16 v[100:103], v[172:175], v[224:227], v[100:103]
	v_mfma_f32_16x16x32_bf16 v[84:87], v[164:167], v[232:235], v[84:87]
	v_mfma_f32_16x16x32_bf16 v[80:83], v[172:175], v[232:235], v[80:83]
	v_mfma_f32_16x16x32_bf16 v[68:71], v[164:167], v[240:243], v[68:71]
	v_mfma_f32_16x16x32_bf16 v[64:67], v[172:175], v[240:243], v[64:67]
	s_barrier
	s_setprio 0
	ds_read_b128 v[176:179], v163 offset:16384
	ds_read_b128 v[188:191], v163 offset:17408
	ds_read_b128 v[220:223], v163 offset:18432
	ds_read_b128 v[224:227], v163 offset:19456
	ds_read_b128 v[228:231], v163 offset:20480
	ds_read_b128 v[232:235], v163 offset:21504
	ds_read_b128 v[236:239], v163 offset:22528
	ds_read_b128 v[240:243], v163 offset:23552
	s_add_u32 s84, s84, 0x100
	s_addc_u32 s85, s85, 0
	s_add_u32 s26, s26, 0x100
	s_addc_u32 s27, s27, 0
	s_add_i32 s66, s97, s10
	s_mov_b32 m0, s66
	v_lshl_add_u64 v[180:181], vcc, 0, v[98:99]
	global_load_lds_dwordx4 v[180:181], off
	s_add_i32 m0, s66, 0x2000
	v_lshl_add_u64 v[192:193], vcc, 0, v[142:143]
	s_add_u32 vcc_lo, vcc_lo, s72
	s_addc_u32 vcc_hi, vcc_hi, 0
	s_add_i32 s0, s0, s10
	global_load_lds_dwordx4 v[192:193], off
	v_lshl_add_u64 v[244:245], vcc, 0, v[98:99]
	s_mov_b32 m0, s0
	v_lshl_add_u64 v[246:247], vcc, 0, v[142:143]
	global_load_lds_dwordx4 v[244:245], off
	s_add_i32 m0, s0, 0x2000
	v_lshl_add_u64 v[248:249], s[86:87], 0, v[96:97]
	global_load_lds_dwordx4 v[246:247], off
	s_mov_b32 m0, s23
	v_lshl_add_u64 v[250:251], s[86:87], 0, v[140:141]
	global_load_lds_dwordx4 v[248:249], off
	s_mov_b32 m0, s33
	s_nop 0
	global_load_lds_dwordx4 v[250:251], off
	s_waitcnt vmcnt(8)
	s_waitcnt lgkmcnt(0)
	s_setprio 1
	s_barrier
	v_mfma_f32_16x16x32_bf16 v[60:63], v[132:135], v[176:179], 0
	v_mfma_f32_16x16x32_bf16 v[56:59], v[148:151], v[176:179], 0
	v_mfma_f32_16x16x32_bf16 v[44:47], v[132:135], v[220:223], 0
	v_mfma_f32_16x16x32_bf16 v[40:43], v[148:151], v[220:223], 0
	v_mfma_f32_16x16x32_bf16 v[28:31], v[132:135], v[228:231], 0
	v_mfma_f32_16x16x32_bf16 v[24:27], v[148:151], v[228:231], 0
	v_mfma_f32_16x16x32_bf16 v[12:15], v[132:135], v[236:239], 0
	v_mfma_f32_16x16x32_bf16 v[8:11], v[148:151], v[236:239], 0
	v_mfma_f32_16x16x32_bf16 v[60:63], v[136:139], v[188:191], v[60:63]
	v_mfma_f32_16x16x32_bf16 v[56:59], v[152:155], v[188:191], v[56:59]
	v_mfma_f32_16x16x32_bf16 v[44:47], v[136:139], v[224:227], v[44:47]
	v_mfma_f32_16x16x32_bf16 v[40:43], v[152:155], v[224:227], v[40:43]
	v_mfma_f32_16x16x32_bf16 v[28:31], v[136:139], v[232:235], v[28:31]
	v_mfma_f32_16x16x32_bf16 v[24:27], v[152:155], v[232:235], v[24:27]
	v_mfma_f32_16x16x32_bf16 v[12:15], v[136:139], v[240:243], v[12:15]
	v_mfma_f32_16x16x32_bf16 v[8:11], v[152:155], v[240:243], v[8:11]
	v_mfma_f32_16x16x32_bf16 v[52:55], v[156:159], v[176:179], 0
	v_mfma_f32_16x16x32_bf16 v[48:51], v[168:171], v[176:179], 0
	v_mfma_f32_16x16x32_bf16 v[36:39], v[156:159], v[220:223], 0
	v_mfma_f32_16x16x32_bf16 v[32:35], v[168:171], v[220:223], 0
	v_mfma_f32_16x16x32_bf16 v[20:23], v[156:159], v[228:231], 0
	v_mfma_f32_16x16x32_bf16 v[16:19], v[168:171], v[228:231], 0
	v_mfma_f32_16x16x32_bf16 v[4:7], v[156:159], v[236:239], 0
	v_mfma_f32_16x16x32_bf16 v[0:3], v[168:171], v[236:239], 0
	v_mfma_f32_16x16x32_bf16 v[52:55], v[164:167], v[188:191], v[52:55]
	v_mfma_f32_16x16x32_bf16 v[48:51], v[172:175], v[188:191], v[48:51]
	v_mfma_f32_16x16x32_bf16 v[36:39], v[164:167], v[224:227], v[36:39]
	v_mfma_f32_16x16x32_bf16 v[32:35], v[172:175], v[224:227], v[32:35]
	v_mfma_f32_16x16x32_bf16 v[20:23], v[164:167], v[232:235], v[20:23]
	v_mfma_f32_16x16x32_bf16 v[16:19], v[172:175], v[232:235], v[16:19]
	v_mfma_f32_16x16x32_bf16 v[4:7], v[164:167], v[240:243], v[4:7]
	v_mfma_f32_16x16x32_bf16 v[0:3], v[172:175], v[240:243], v[0:3]
	s_barrier
	s_setprio 0
	v_add_u32_e32 v152, 0x18000, v161
	v_add_u32_e32 v172, 0x1c000, v161
	ds_read_b128 v[132:135], v152
	ds_read_b128 v[136:139], v152 offset:1024
	ds_read_b128 v[148:151], v152 offset:2048
	ds_read_b128 v[152:155], v152 offset:3072
	ds_read_b128 v[156:159], v172
	ds_read_b128 v[164:167], v172 offset:1024
	ds_read_b128 v[168:171], v172 offset:2048
	ds_read_b128 v[172:175], v172 offset:3072
	s_add_i32 s0, 0, 0x18000
	s_add_i32 s66, 0, 0x1c000
	s_add_u32 s86, s86, s72
	s_addc_u32 s87, s87, 0
	s_mov_b32 m0, s43
	v_lshl_add_u64 v[252:253], s[86:87], 0, v[96:97]
	ds_read_b128 v[176:179], v163 offset:32768
	ds_read_b128 v[188:191], v163 offset:33792
	ds_read_b128 v[220:223], v163 offset:34816
	ds_read_b128 v[224:227], v163 offset:35840
	ds_read_b128 v[228:231], v163 offset:36864
	ds_read_b128 v[232:235], v163 offset:37888
	ds_read_b128 v[236:239], v163 offset:38912
	ds_read_b128 v[240:243], v163 offset:39936
	global_load_lds_dwordx4 v[252:253], off
	v_lshl_add_u64 v[252:253], s[86:87], 0, v[140:141]
	s_mov_b32 m0, s44
	s_nop 0
	global_load_lds_dwordx4 v[252:253], off
	s_waitcnt vmcnt(8)
	s_waitcnt lgkmcnt(0)
	s_setprio 1
	s_barrier
	v_mfma_f32_16x16x32_bf16 v[128:131], v[132:135], v[176:179], v[128:131]
	v_mfma_f32_16x16x32_bf16 v[124:127], v[148:151], v[176:179], v[124:127]
	v_mfma_f32_16x16x32_bf16 v[112:115], v[132:135], v[220:223], v[112:115]
	v_mfma_f32_16x16x32_bf16 v[108:111], v[148:151], v[220:223], v[108:111]
	v_mfma_f32_16x16x32_bf16 v[92:95], v[132:135], v[228:231], v[92:95]
	v_mfma_f32_16x16x32_bf16 v[88:91], v[148:151], v[228:231], v[88:91]
	v_mfma_f32_16x16x32_bf16 v[76:79], v[132:135], v[236:239], v[76:79]
	v_mfma_f32_16x16x32_bf16 v[72:75], v[148:151], v[236:239], v[72:75]
	v_mfma_f32_16x16x32_bf16 v[128:131], v[136:139], v[188:191], v[128:131]
	v_mfma_f32_16x16x32_bf16 v[124:127], v[152:155], v[188:191], v[124:127]
	v_mfma_f32_16x16x32_bf16 v[112:115], v[136:139], v[224:227], v[112:115]
	v_mfma_f32_16x16x32_bf16 v[108:111], v[152:155], v[224:227], v[108:111]
	v_mfma_f32_16x16x32_bf16 v[92:95], v[136:139], v[232:235], v[92:95]
	v_mfma_f32_16x16x32_bf16 v[88:91], v[152:155], v[232:235], v[88:91]
	v_mfma_f32_16x16x32_bf16 v[76:79], v[136:139], v[240:243], v[76:79]
	v_mfma_f32_16x16x32_bf16 v[72:75], v[152:155], v[240:243], v[72:75]
	v_mfma_f32_16x16x32_bf16 v[120:123], v[156:159], v[176:179], v[120:123]
	v_mfma_f32_16x16x32_bf16 v[116:119], v[168:171], v[176:179], v[116:119]
	v_mfma_f32_16x16x32_bf16 v[104:107], v[156:159], v[220:223], v[104:107]
	v_mfma_f32_16x16x32_bf16 v[100:103], v[168:171], v[220:223], v[100:103]
	v_mfma_f32_16x16x32_bf16 v[84:87], v[156:159], v[228:231], v[84:87]
	v_mfma_f32_16x16x32_bf16 v[80:83], v[168:171], v[228:231], v[80:83]
	v_mfma_f32_16x16x32_bf16 v[68:71], v[156:159], v[236:239], v[68:71]
	v_mfma_f32_16x16x32_bf16 v[64:67], v[168:171], v[236:239], v[64:67]
	v_mfma_f32_16x16x32_bf16 v[120:123], v[164:167], v[188:191], v[120:123]
	v_mfma_f32_16x16x32_bf16 v[116:119], v[172:175], v[188:191], v[116:119]
	v_mfma_f32_16x16x32_bf16 v[104:107], v[164:167], v[224:227], v[104:107]
	v_mfma_f32_16x16x32_bf16 v[100:103], v[172:175], v[224:227], v[100:103]
	v_mfma_f32_16x16x32_bf16 v[84:87], v[164:167], v[232:235], v[84:87]
	v_mfma_f32_16x16x32_bf16 v[80:83], v[172:175], v[232:235], v[80:83]
	v_mfma_f32_16x16x32_bf16 v[68:71], v[164:167], v[240:243], v[68:71]
	v_mfma_f32_16x16x32_bf16 v[64:67], v[172:175], v[240:243], v[64:67]
	s_barrier
	s_setprio 0
	ds_read_b128 v[176:179], v163 offset:49152
	ds_read_b128 v[188:191], v163 offset:50176
	ds_read_b128 v[220:223], v163 offset:51200
	ds_read_b128 v[224:227], v163 offset:52224
	ds_read_b128 v[228:231], v163 offset:53248
	ds_read_b128 v[232:235], v163 offset:54272
	ds_read_b128 v[236:239], v163 offset:55296
	ds_read_b128 v[240:243], v163 offset:56320
	s_add_i32 s0, s0, s10
	s_mov_b32 m0, s0
	v_lshl_add_u64 v[180:181], v[180:181], 0, s[58:59]
	global_load_lds_dwordx4 v[180:181], off
	v_lshl_add_u64 v[180:181], v[192:193], 0, s[58:59]
	s_add_i32 m0, s0, 0x2000
	s_add_i32 s0, s66, s10
	global_load_lds_dwordx4 v[180:181], off
	v_lshl_add_u64 v[180:181], v[244:245], 0, s[58:59]
	s_mov_b32 m0, s0
	s_nop 0
	global_load_lds_dwordx4 v[180:181], off
	v_lshl_add_u64 v[180:181], v[246:247], 0, s[58:59]
	s_add_i32 m0, s0, 0x2000
	s_nop 0
	global_load_lds_dwordx4 v[180:181], off
	v_lshl_add_u64 v[180:181], v[248:249], 0, s[58:59]
	s_mov_b32 m0, s47
	s_nop 0
	global_load_lds_dwordx4 v[180:181], off
	v_lshl_add_u64 v[180:181], v[250:251], 0, s[58:59]
	s_mov_b32 m0, s56
	s_nop 0
	global_load_lds_dwordx4 v[180:181], off
	s_waitcnt vmcnt(8)
	s_waitcnt lgkmcnt(0)
	s_setprio 1
	s_barrier
	v_mfma_f32_16x16x32_bf16 v[60:63], v[132:135], v[176:179], v[60:63]
	v_mfma_f32_16x16x32_bf16 v[56:59], v[148:151], v[176:179], v[56:59]
	v_mfma_f32_16x16x32_bf16 v[44:47], v[132:135], v[220:223], v[44:47]
	v_mfma_f32_16x16x32_bf16 v[40:43], v[148:151], v[220:223], v[40:43]
	v_mfma_f32_16x16x32_bf16 v[28:31], v[132:135], v[228:231], v[28:31]
	v_mfma_f32_16x16x32_bf16 v[24:27], v[148:151], v[228:231], v[24:27]
	v_mfma_f32_16x16x32_bf16 v[12:15], v[132:135], v[236:239], v[12:15]
	v_mfma_f32_16x16x32_bf16 v[8:11], v[148:151], v[236:239], v[8:11]
	v_mfma_f32_16x16x32_bf16 v[60:63], v[136:139], v[188:191], v[60:63]
	v_mfma_f32_16x16x32_bf16 v[56:59], v[152:155], v[188:191], v[56:59]
	v_mfma_f32_16x16x32_bf16 v[44:47], v[136:139], v[224:227], v[44:47]
	v_mfma_f32_16x16x32_bf16 v[40:43], v[152:155], v[224:227], v[40:43]
	v_mfma_f32_16x16x32_bf16 v[28:31], v[136:139], v[232:235], v[28:31]
	v_mfma_f32_16x16x32_bf16 v[24:27], v[152:155], v[232:235], v[24:27]
	v_mfma_f32_16x16x32_bf16 v[12:15], v[136:139], v[240:243], v[12:15]
	v_mfma_f32_16x16x32_bf16 v[8:11], v[152:155], v[240:243], v[8:11]
	v_mfma_f32_16x16x32_bf16 v[52:55], v[156:159], v[176:179], v[52:55]
	v_mfma_f32_16x16x32_bf16 v[48:51], v[168:171], v[176:179], v[48:51]
	v_mfma_f32_16x16x32_bf16 v[36:39], v[156:159], v[220:223], v[36:39]
	v_mfma_f32_16x16x32_bf16 v[32:35], v[168:171], v[220:223], v[32:35]
	v_mfma_f32_16x16x32_bf16 v[20:23], v[156:159], v[228:231], v[20:23]
	v_mfma_f32_16x16x32_bf16 v[16:19], v[168:171], v[228:231], v[16:19]
	v_mfma_f32_16x16x32_bf16 v[4:7], v[156:159], v[236:239], v[4:7]
	v_mfma_f32_16x16x32_bf16 v[0:3], v[168:171], v[236:239], v[0:3]
	v_mfma_f32_16x16x32_bf16 v[52:55], v[164:167], v[188:191], v[52:55]
	v_mfma_f32_16x16x32_bf16 v[48:51], v[172:175], v[188:191], v[48:51]
	v_mfma_f32_16x16x32_bf16 v[36:39], v[164:167], v[224:227], v[36:39]
	v_mfma_f32_16x16x32_bf16 v[32:35], v[172:175], v[224:227], v[32:35]
	v_mfma_f32_16x16x32_bf16 v[20:23], v[164:167], v[232:235], v[20:23]
	v_mfma_f32_16x16x32_bf16 v[16:19], v[172:175], v[232:235], v[16:19]
	v_mfma_f32_16x16x32_bf16 v[4:7], v[164:167], v[240:243], v[4:7]
	v_mfma_f32_16x16x32_bf16 v[0:3], v[172:175], v[240:243], v[0:3]
	s_barrier
	s_setprio 0
	s_cmp_ge_u32 s42, s67
	s_mov_b32 s0, s42
	s_cbranch_scc1 .Lpeel_exit_310
.LBB0_310:
	v_add_u32_e32 v152, 0x10000, v161
	v_add_u32_e32 v172, 0x14000, v161
	ds_read_b128 v[132:135], v152
	ds_read_b128 v[136:139], v152 offset:1024
	ds_read_b128 v[148:151], v152 offset:2048
	ds_read_b128 v[152:155], v152 offset:3072
	ds_read_b128 v[156:159], v172
	ds_read_b128 v[164:167], v172 offset:1024
	ds_read_b128 v[168:171], v172 offset:2048
	ds_read_b128 v[172:175], v172 offset:3072
	s_add_i32 s42, s0, 2
	s_add_u32 s66, s84, 0x80
	s_addc_u32 s86, s85, 0
	s_add_i32 s97, 0, 0x10000
	s_cmp_eq_u32 s88, s0
	s_cselect_b32 s87, s81, s86
	s_cselect_b32 s86, s80, s66
	s_cselect_b32 vcc_hi, s83, s27
	s_cselect_b32 vcc_lo, s82, s26
	s_add_i32 s0, 0, 0x14000
	v_lshl_add_u64 v[180:181], s[84:85], 0, v[144:145]
	s_add_i32 m0, s23, 0xc000
	ds_read_b128 v[176:179], v163
	ds_read_b128 v[188:191], v163 offset:1024
	ds_read_b128 v[220:223], v163 offset:2048
	ds_read_b128 v[224:227], v163 offset:3072
	ds_read_b128 v[228:231], v163 offset:4096
	ds_read_b128 v[232:235], v163 offset:5120
	ds_read_b128 v[236:239], v163 offset:6144
	ds_read_b128 v[240:243], v163 offset:7168
	global_load_lds_dwordx4 v[180:181], off
	v_lshl_add_u64 v[180:181], s[84:85], 0, v[146:147]
	s_add_i32 m0, s23, 0xe000
	s_nop 0
	global_load_lds_dwordx4 v[180:181], off
	s_waitcnt vmcnt(8)
	s_waitcnt lgkmcnt(0)
	s_setprio 1
	s_barrier
	v_mfma_f32_16x16x32_bf16 v[128:131], v[132:135], v[176:179], v[128:131]
	v_mfma_f32_16x16x32_bf16 v[124:127], v[148:151], v[176:179], v[124:127]
	v_mfma_f32_16x16x32_bf16 v[112:115], v[132:135], v[220:223], v[112:115]
	v_mfma_f32_16x16x32_bf16 v[108:111], v[148:151], v[220:223], v[108:111]
	v_mfma_f32_16x16x32_bf16 v[92:95], v[132:135], v[228:231], v[92:95]
	v_mfma_f32_16x16x32_bf16 v[88:91], v[148:151], v[228:231], v[88:91]
	v_mfma_f32_16x16x32_bf16 v[76:79], v[132:135], v[236:239], v[76:79]
	v_mfma_f32_16x16x32_bf16 v[72:75], v[148:151], v[236:239], v[72:75]
	v_mfma_f32_16x16x32_bf16 v[128:131], v[136:139], v[188:191], v[128:131]
	v_mfma_f32_16x16x32_bf16 v[124:127], v[152:155], v[188:191], v[124:127]
	v_mfma_f32_16x16x32_bf16 v[112:115], v[136:139], v[224:227], v[112:115]
	v_mfma_f32_16x16x32_bf16 v[108:111], v[152:155], v[224:227], v[108:111]
	v_mfma_f32_16x16x32_bf16 v[92:95], v[136:139], v[232:235], v[92:95]
	v_mfma_f32_16x16x32_bf16 v[88:91], v[152:155], v[232:235], v[88:91]
	v_mfma_f32_16x16x32_bf16 v[76:79], v[136:139], v[240:243], v[76:79]
	v_mfma_f32_16x16x32_bf16 v[72:75], v[152:155], v[240:243], v[72:75]
	v_mfma_f32_16x16x32_bf16 v[120:123], v[156:159], v[176:179], v[120:123]
	v_mfma_f32_16x16x32_bf16 v[116:119], v[168:171], v[176:179], v[116:119]
	v_mfma_f32_16x16x32_bf16 v[104:107], v[156:159], v[220:223], v[104:107]
	v_mfma_f32_16x16x32_bf16 v[100:103], v[168:171], v[220:223], v[100:103]
	v_mfma_f32_16x16x32_bf16 v[84:87], v[156:159], v[228:231], v[84:87]
	v_mfma_f32_16x16x32_bf16 v[80:83], v[168:171], v[228:231], v[80:83]
	v_mfma_f32_16x16x32_bf16 v[68:71], v[156:159], v[236:239], v[68:71]
	v_mfma_f32_16x16x32_bf16 v[64:67], v[168:171], v[236:239], v[64:67]
	v_mfma_f32_16x16x32_bf16 v[120:123], v[164:167], v[188:191], v[120:123]
	v_mfma_f32_16x16x32_bf16 v[116:119], v[172:175], v[188:191], v[116:119]
	v_mfma_f32_16x16x32_bf16 v[104:107], v[164:167], v[224:227], v[104:107]
	v_mfma_f32_16x16x32_bf16 v[100:103], v[172:175], v[224:227], v[100:103]
	v_mfma_f32_16x16x32_bf16 v[84:87], v[164:167], v[232:235], v[84:87]
	v_mfma_f32_16x16x32_bf16 v[80:83], v[172:175], v[232:235], v[80:83]
	v_mfma_f32_16x16x32_bf16 v[68:71], v[164:167], v[240:243], v[68:71]
	v_mfma_f32_16x16x32_bf16 v[64:67], v[172:175], v[240:243], v[64:67]
	s_barrier
	s_setprio 0
	ds_read_b128 v[176:179], v163 offset:16384
	ds_read_b128 v[188:191], v163 offset:17408
	ds_read_b128 v[220:223], v163 offset:18432
	ds_read_b128 v[224:227], v163 offset:19456
	ds_read_b128 v[228:231], v163 offset:20480
	ds_read_b128 v[232:235], v163 offset:21504
	ds_read_b128 v[236:239], v163 offset:22528
	ds_read_b128 v[240:243], v163 offset:23552
	s_add_u32 s84, s84, 0x100
	s_addc_u32 s85, s85, 0
	s_add_u32 s26, s26, 0x100
	s_addc_u32 s27, s27, 0
	s_add_i32 s66, s97, s10
	s_mov_b32 m0, s66
	v_lshl_add_u64 v[180:181], vcc, 0, v[98:99]
	global_load_lds_dwordx4 v[180:181], off
	s_add_i32 m0, s66, 0x2000
	v_lshl_add_u64 v[192:193], vcc, 0, v[142:143]
	s_add_u32 vcc_lo, vcc_lo, s72
	s_addc_u32 vcc_hi, vcc_hi, 0
	s_add_i32 s0, s0, s10
	global_load_lds_dwordx4 v[192:193], off
	v_lshl_add_u64 v[244:245], vcc, 0, v[98:99]
	s_mov_b32 m0, s0
	v_lshl_add_u64 v[246:247], vcc, 0, v[142:143]
	global_load_lds_dwordx4 v[244:245], off
	s_add_i32 m0, s0, 0x2000
	v_lshl_add_u64 v[248:249], s[86:87], 0, v[96:97]
	global_load_lds_dwordx4 v[246:247], off
	s_mov_b32 m0, s23
	v_lshl_add_u64 v[250:251], s[86:87], 0, v[140:141]
	global_load_lds_dwordx4 v[248:249], off
	s_mov_b32 m0, s33
	s_nop 0
	global_load_lds_dwordx4 v[250:251], off
	s_waitcnt vmcnt(8)
	s_waitcnt lgkmcnt(0)
	s_setprio 1
	s_barrier
	v_mfma_f32_16x16x32_bf16 v[60:63], v[132:135], v[176:179], v[60:63]
	v_mfma_f32_16x16x32_bf16 v[56:59], v[148:151], v[176:179], v[56:59]
	v_mfma_f32_16x16x32_bf16 v[44:47], v[132:135], v[220:223], v[44:47]
	v_mfma_f32_16x16x32_bf16 v[40:43], v[148:151], v[220:223], v[40:43]
	v_mfma_f32_16x16x32_bf16 v[28:31], v[132:135], v[228:231], v[28:31]
	v_mfma_f32_16x16x32_bf16 v[24:27], v[148:151], v[228:231], v[24:27]
	v_mfma_f32_16x16x32_bf16 v[12:15], v[132:135], v[236:239], v[12:15]
	v_mfma_f32_16x16x32_bf16 v[8:11], v[148:151], v[236:239], v[8:11]
	v_mfma_f32_16x16x32_bf16 v[60:63], v[136:139], v[188:191], v[60:63]
	v_mfma_f32_16x16x32_bf16 v[56:59], v[152:155], v[188:191], v[56:59]
	v_mfma_f32_16x16x32_bf16 v[44:47], v[136:139], v[224:227], v[44:47]
	v_mfma_f32_16x16x32_bf16 v[40:43], v[152:155], v[224:227], v[40:43]
	v_mfma_f32_16x16x32_bf16 v[28:31], v[136:139], v[232:235], v[28:31]
	v_mfma_f32_16x16x32_bf16 v[24:27], v[152:155], v[232:235], v[24:27]
	v_mfma_f32_16x16x32_bf16 v[12:15], v[136:139], v[240:243], v[12:15]
	v_mfma_f32_16x16x32_bf16 v[8:11], v[152:155], v[240:243], v[8:11]
	v_mfma_f32_16x16x32_bf16 v[52:55], v[156:159], v[176:179], v[52:55]
	v_mfma_f32_16x16x32_bf16 v[48:51], v[168:171], v[176:179], v[48:51]
	v_mfma_f32_16x16x32_bf16 v[36:39], v[156:159], v[220:223], v[36:39]
	v_mfma_f32_16x16x32_bf16 v[32:35], v[168:171], v[220:223], v[32:35]
	v_mfma_f32_16x16x32_bf16 v[20:23], v[156:159], v[228:231], v[20:23]
	v_mfma_f32_16x16x32_bf16 v[16:19], v[168:171], v[228:231], v[16:19]
	v_mfma_f32_16x16x32_bf16 v[4:7], v[156:159], v[236:239], v[4:7]
	v_mfma_f32_16x16x32_bf16 v[0:3], v[168:171], v[236:239], v[0:3]
	v_mfma_f32_16x16x32_bf16 v[52:55], v[164:167], v[188:191], v[52:55]
	v_mfma_f32_16x16x32_bf16 v[48:51], v[172:175], v[188:191], v[48:51]
	v_mfma_f32_16x16x32_bf16 v[36:39], v[164:167], v[224:227], v[36:39]
	v_mfma_f32_16x16x32_bf16 v[32:35], v[172:175], v[224:227], v[32:35]
	v_mfma_f32_16x16x32_bf16 v[20:23], v[164:167], v[232:235], v[20:23]
	v_mfma_f32_16x16x32_bf16 v[16:19], v[172:175], v[232:235], v[16:19]
	v_mfma_f32_16x16x32_bf16 v[4:7], v[164:167], v[240:243], v[4:7]
	v_mfma_f32_16x16x32_bf16 v[0:3], v[172:175], v[240:243], v[0:3]
	s_barrier
	s_setprio 0
	v_add_u32_e32 v152, 0x18000, v161
	v_add_u32_e32 v172, 0x1c000, v161
	ds_read_b128 v[132:135], v152
	ds_read_b128 v[136:139], v152 offset:1024
	ds_read_b128 v[148:151], v152 offset:2048
	ds_read_b128 v[152:155], v152 offset:3072
	ds_read_b128 v[156:159], v172
	ds_read_b128 v[164:167], v172 offset:1024
	ds_read_b128 v[168:171], v172 offset:2048
	ds_read_b128 v[172:175], v172 offset:3072
	s_add_i32 s0, 0, 0x18000
	s_add_i32 s66, 0, 0x1c000
	s_add_u32 s86, s86, s72
	s_addc_u32 s87, s87, 0
	s_mov_b32 m0, s43
	v_lshl_add_u64 v[252:253], s[86:87], 0, v[96:97]
	ds_read_b128 v[176:179], v163 offset:32768
	ds_read_b128 v[188:191], v163 offset:33792
	ds_read_b128 v[220:223], v163 offset:34816
	ds_read_b128 v[224:227], v163 offset:35840
	ds_read_b128 v[228:231], v163 offset:36864
	ds_read_b128 v[232:235], v163 offset:37888
	ds_read_b128 v[236:239], v163 offset:38912
	ds_read_b128 v[240:243], v163 offset:39936
	global_load_lds_dwordx4 v[252:253], off
	v_lshl_add_u64 v[252:253], s[86:87], 0, v[140:141]
	s_mov_b32 m0, s44
	s_nop 0
	global_load_lds_dwordx4 v[252:253], off
	s_waitcnt vmcnt(8)
	s_waitcnt lgkmcnt(0)
	s_setprio 1
	s_barrier
	v_mfma_f32_16x16x32_bf16 v[128:131], v[132:135], v[176:179], v[128:131]
	v_mfma_f32_16x16x32_bf16 v[124:127], v[148:151], v[176:179], v[124:127]
	v_mfma_f32_16x16x32_bf16 v[112:115], v[132:135], v[220:223], v[112:115]
	v_mfma_f32_16x16x32_bf16 v[108:111], v[148:151], v[220:223], v[108:111]
	v_mfma_f32_16x16x32_bf16 v[92:95], v[132:135], v[228:231], v[92:95]
	v_mfma_f32_16x16x32_bf16 v[88:91], v[148:151], v[228:231], v[88:91]
	v_mfma_f32_16x16x32_bf16 v[76:79], v[132:135], v[236:239], v[76:79]
	v_mfma_f32_16x16x32_bf16 v[72:75], v[148:151], v[236:239], v[72:75]
	v_mfma_f32_16x16x32_bf16 v[128:131], v[136:139], v[188:191], v[128:131]
	v_mfma_f32_16x16x32_bf16 v[124:127], v[152:155], v[188:191], v[124:127]
	v_mfma_f32_16x16x32_bf16 v[112:115], v[136:139], v[224:227], v[112:115]
	v_mfma_f32_16x16x32_bf16 v[108:111], v[152:155], v[224:227], v[108:111]
	v_mfma_f32_16x16x32_bf16 v[92:95], v[136:139], v[232:235], v[92:95]
	v_mfma_f32_16x16x32_bf16 v[88:91], v[152:155], v[232:235], v[88:91]
	v_mfma_f32_16x16x32_bf16 v[76:79], v[136:139], v[240:243], v[76:79]
	v_mfma_f32_16x16x32_bf16 v[72:75], v[152:155], v[240:243], v[72:75]
	v_mfma_f32_16x16x32_bf16 v[120:123], v[156:159], v[176:179], v[120:123]
	v_mfma_f32_16x16x32_bf16 v[116:119], v[168:171], v[176:179], v[116:119]
	v_mfma_f32_16x16x32_bf16 v[104:107], v[156:159], v[220:223], v[104:107]
	v_mfma_f32_16x16x32_bf16 v[100:103], v[168:171], v[220:223], v[100:103]
	v_mfma_f32_16x16x32_bf16 v[84:87], v[156:159], v[228:231], v[84:87]
	v_mfma_f32_16x16x32_bf16 v[80:83], v[168:171], v[228:231], v[80:83]
	v_mfma_f32_16x16x32_bf16 v[68:71], v[156:159], v[236:239], v[68:71]
	v_mfma_f32_16x16x32_bf16 v[64:67], v[168:171], v[236:239], v[64:67]
	v_mfma_f32_16x16x32_bf16 v[120:123], v[164:167], v[188:191], v[120:123]
	v_mfma_f32_16x16x32_bf16 v[116:119], v[172:175], v[188:191], v[116:119]
	v_mfma_f32_16x16x32_bf16 v[104:107], v[164:167], v[224:227], v[104:107]
	v_mfma_f32_16x16x32_bf16 v[100:103], v[172:175], v[224:227], v[100:103]
	v_mfma_f32_16x16x32_bf16 v[84:87], v[164:167], v[232:235], v[84:87]
	v_mfma_f32_16x16x32_bf16 v[80:83], v[172:175], v[232:235], v[80:83]
	v_mfma_f32_16x16x32_bf16 v[68:71], v[164:167], v[240:243], v[68:71]
	v_mfma_f32_16x16x32_bf16 v[64:67], v[172:175], v[240:243], v[64:67]
	s_barrier
	s_setprio 0
	ds_read_b128 v[176:179], v163 offset:49152
	ds_read_b128 v[188:191], v163 offset:50176
	ds_read_b128 v[220:223], v163 offset:51200
	ds_read_b128 v[224:227], v163 offset:52224
	ds_read_b128 v[228:231], v163 offset:53248
	ds_read_b128 v[232:235], v163 offset:54272
	ds_read_b128 v[236:239], v163 offset:55296
	ds_read_b128 v[240:243], v163 offset:56320
	s_add_i32 s0, s0, s10
	s_mov_b32 m0, s0
	v_lshl_add_u64 v[180:181], v[180:181], 0, s[58:59]
	global_load_lds_dwordx4 v[180:181], off
	v_lshl_add_u64 v[180:181], v[192:193], 0, s[58:59]
	s_add_i32 m0, s0, 0x2000
	s_add_i32 s0, s66, s10
	global_load_lds_dwordx4 v[180:181], off
	v_lshl_add_u64 v[180:181], v[244:245], 0, s[58:59]
	s_mov_b32 m0, s0
	s_nop 0
	global_load_lds_dwordx4 v[180:181], off
	v_lshl_add_u64 v[180:181], v[246:247], 0, s[58:59]
	s_add_i32 m0, s0, 0x2000
	s_nop 0
	global_load_lds_dwordx4 v[180:181], off
	v_lshl_add_u64 v[180:181], v[248:249], 0, s[58:59]
	s_mov_b32 m0, s47
	s_nop 0
	global_load_lds_dwordx4 v[180:181], off
	v_lshl_add_u64 v[180:181], v[250:251], 0, s[58:59]
	s_mov_b32 m0, s56
	s_nop 0
	global_load_lds_dwordx4 v[180:181], off
	s_waitcnt vmcnt(8)
	s_waitcnt lgkmcnt(0)
	s_setprio 1
	s_barrier
	v_mfma_f32_16x16x32_bf16 v[60:63], v[132:135], v[176:179], v[60:63]
	v_mfma_f32_16x16x32_bf16 v[56:59], v[148:151], v[176:179], v[56:59]
	v_mfma_f32_16x16x32_bf16 v[44:47], v[132:135], v[220:223], v[44:47]
	v_mfma_f32_16x16x32_bf16 v[40:43], v[148:151], v[220:223], v[40:43]
	v_mfma_f32_16x16x32_bf16 v[28:31], v[132:135], v[228:231], v[28:31]
	v_mfma_f32_16x16x32_bf16 v[24:27], v[148:151], v[228:231], v[24:27]
	v_mfma_f32_16x16x32_bf16 v[12:15], v[132:135], v[236:239], v[12:15]
	v_mfma_f32_16x16x32_bf16 v[8:11], v[148:151], v[236:239], v[8:11]
	v_mfma_f32_16x16x32_bf16 v[60:63], v[136:139], v[188:191], v[60:63]
	v_mfma_f32_16x16x32_bf16 v[56:59], v[152:155], v[188:191], v[56:59]
	v_mfma_f32_16x16x32_bf16 v[44:47], v[136:139], v[224:227], v[44:47]
	v_mfma_f32_16x16x32_bf16 v[40:43], v[152:155], v[224:227], v[40:43]
	v_mfma_f32_16x16x32_bf16 v[28:31], v[136:139], v[232:235], v[28:31]
	v_mfma_f32_16x16x32_bf16 v[24:27], v[152:155], v[232:235], v[24:27]
	v_mfma_f32_16x16x32_bf16 v[12:15], v[136:139], v[240:243], v[12:15]
	v_mfma_f32_16x16x32_bf16 v[8:11], v[152:155], v[240:243], v[8:11]
	v_mfma_f32_16x16x32_bf16 v[52:55], v[156:159], v[176:179], v[52:55]
	v_mfma_f32_16x16x32_bf16 v[48:51], v[168:171], v[176:179], v[48:51]
	v_mfma_f32_16x16x32_bf16 v[36:39], v[156:159], v[220:223], v[36:39]
	v_mfma_f32_16x16x32_bf16 v[32:35], v[168:171], v[220:223], v[32:35]
	v_mfma_f32_16x16x32_bf16 v[20:23], v[156:159], v[228:231], v[20:23]
	v_mfma_f32_16x16x32_bf16 v[16:19], v[168:171], v[228:231], v[16:19]
	v_mfma_f32_16x16x32_bf16 v[4:7], v[156:159], v[236:239], v[4:7]
	v_mfma_f32_16x16x32_bf16 v[0:3], v[168:171], v[236:239], v[0:3]
	v_mfma_f32_16x16x32_bf16 v[52:55], v[164:167], v[188:191], v[52:55]
	v_mfma_f32_16x16x32_bf16 v[48:51], v[172:175], v[188:191], v[48:51]
	v_mfma_f32_16x16x32_bf16 v[36:39], v[164:167], v[224:227], v[36:39]
	v_mfma_f32_16x16x32_bf16 v[32:35], v[172:175], v[224:227], v[32:35]
	v_mfma_f32_16x16x32_bf16 v[20:23], v[164:167], v[232:235], v[20:23]
	v_mfma_f32_16x16x32_bf16 v[16:19], v[172:175], v[232:235], v[16:19]
	v_mfma_f32_16x16x32_bf16 v[4:7], v[164:167], v[240:243], v[4:7]
	v_mfma_f32_16x16x32_bf16 v[0:3], v[172:175], v[240:243], v[0:3]
	s_barrier
	s_setprio 0
	s_cmp_ge_u32 s42, s67
	s_mov_b32 s0, s42
	s_cbranch_scc0 .LBB0_310

.LBB0_345:
	s_ashr_i32 s71, s70, 31
	s_lshl_b64 s[56:57], s[70:71], 19
	s_add_u32 s74, s12, s56
	s_addc_u32 s75, s13, s57
	s_and_b64 s[56:57], s[72:73], exec
	s_cselect_b32 s27, s75, s79
	s_cselect_b32 s42, s74, s78
	s_ashr_i32 s69, s68, 31
	s_lshl_b64 s[56:57], s[68:69], 19
	s_add_u32 s76, s4, s56
	s_addc_u32 s77, s5, s57
	s_and_b64 s[56:57], s[72:73], exec
	s_cselect_b32 s56, s77, s81
	s_cselect_b32 s57, s76, s80
	s_add_u32 s78, s78, 0x40080
	s_addc_u32 s79, s79, 0
	s_add_u32 s69, s80, 0x100
	s_addc_u32 s71, s81, 0
	s_mov_b32 s84, -2
	s_waitcnt vmcnt(0)
	v_add_u32_e32 v160, 0x10000, v145
	v_add_u32_e32 v176, 0x14000, v145
	ds_read_b128 v[140:143], v160
	ds_read_b128 v[152:155], v160 offset:1024
	ds_read_b128 v[156:159], v160 offset:2048
	ds_read_b128 v[160:163], v160 offset:3072
	ds_read_b128 v[164:167], v176
	ds_read_b128 v[168:171], v176 offset:1024
	ds_read_b128 v[172:175], v176 offset:2048
	ds_read_b128 v[176:179], v176 offset:3072
	s_add_u32 s80, s78, 0xfffc0080
	s_addc_u32 s81, s79, -1
	s_add_i32 s85, 0, 0x10000
	s_cmp_eq_u32 s84, 12
	s_cselect_b32 s83, s27, s81
	s_cselect_b32 s82, s42, s80
	s_cselect_b32 s81, s56, s71
	s_cselect_b32 s80, s57, s69
	s_add_i32 s88, 0, 0x14000
	v_lshl_add_u64 v[180:181], s[78:79], 0, v[136:137]
	s_add_i32 m0, s11, 0xc000
	ds_read_b128 v[188:191], v151
	ds_read_b128 v[220:223], v151 offset:1024
	ds_read_b128 v[224:227], v151 offset:2048
	ds_read_b128 v[228:231], v151 offset:3072
	ds_read_b128 v[232:235], v151 offset:4096
	ds_read_b128 v[236:239], v151 offset:5120
	ds_read_b128 v[240:243], v151 offset:6144
	ds_read_b128 v[244:247], v151 offset:7168
	global_load_lds_dwordx4 v[180:181], off
	v_lshl_add_u64 v[180:181], s[78:79], 0, v[138:139]
	s_add_i32 m0, s11, 0xe000
	s_nop 0
	global_load_lds_dwordx4 v[180:181], off
	s_waitcnt vmcnt(8)
	s_waitcnt lgkmcnt(0)
	s_setprio 1
	s_barrier
	v_mfma_f32_16x16x32_bf16 v[128:131], v[140:143], v[188:191], 0
	v_mfma_f32_16x16x32_bf16 v[120:123], v[156:159], v[188:191], 0
	v_mfma_f32_16x16x32_bf16 v[112:115], v[140:143], v[224:227], 0
	v_mfma_f32_16x16x32_bf16 v[104:107], v[156:159], v[224:227], 0
	v_mfma_f32_16x16x32_bf16 v[92:95], v[140:143], v[232:235], 0
	v_mfma_f32_16x16x32_bf16 v[84:87], v[156:159], v[232:235], 0
	v_mfma_f32_16x16x32_bf16 v[76:79], v[140:143], v[240:243], 0
	v_mfma_f32_16x16x32_bf16 v[68:71], v[156:159], v[240:243], 0
	v_mfma_f32_16x16x32_bf16 v[128:131], v[152:155], v[220:223], v[128:131]
	v_mfma_f32_16x16x32_bf16 v[120:123], v[160:163], v[220:223], v[120:123]
	v_mfma_f32_16x16x32_bf16 v[112:115], v[152:155], v[228:231], v[112:115]
	v_mfma_f32_16x16x32_bf16 v[104:107], v[160:163], v[228:231], v[104:107]
	v_mfma_f32_16x16x32_bf16 v[92:95], v[152:155], v[236:239], v[92:95]
	v_mfma_f32_16x16x32_bf16 v[84:87], v[160:163], v[236:239], v[84:87]
	v_mfma_f32_16x16x32_bf16 v[76:79], v[152:155], v[244:247], v[76:79]
	v_mfma_f32_16x16x32_bf16 v[68:71], v[160:163], v[244:247], v[68:71]
	v_mfma_f32_16x16x32_bf16 v[124:127], v[164:167], v[188:191], 0
	v_mfma_f32_16x16x32_bf16 v[116:119], v[172:175], v[188:191], 0
	v_mfma_f32_16x16x32_bf16 v[108:111], v[164:167], v[224:227], 0
	v_mfma_f32_16x16x32_bf16 v[100:103], v[172:175], v[224:227], 0
	v_mfma_f32_16x16x32_bf16 v[88:91], v[164:167], v[232:235], 0
	v_mfma_f32_16x16x32_bf16 v[80:83], v[172:175], v[232:235], 0
	v_mfma_f32_16x16x32_bf16 v[72:75], v[164:167], v[240:243], 0
	v_mfma_f32_16x16x32_bf16 v[64:67], v[172:175], v[240:243], 0
	v_mfma_f32_16x16x32_bf16 v[124:127], v[168:171], v[220:223], v[124:127]
	v_mfma_f32_16x16x32_bf16 v[116:119], v[176:179], v[220:223], v[116:119]
	v_mfma_f32_16x16x32_bf16 v[108:111], v[168:171], v[228:231], v[108:111]
	v_mfma_f32_16x16x32_bf16 v[100:103], v[176:179], v[228:231], v[100:103]
	v_mfma_f32_16x16x32_bf16 v[88:91], v[168:171], v[236:239], v[88:91]
	v_mfma_f32_16x16x32_bf16 v[80:83], v[176:179], v[236:239], v[80:83]
	v_mfma_f32_16x16x32_bf16 v[72:75], v[168:171], v[244:247], v[72:75]
	v_mfma_f32_16x16x32_bf16 v[64:67], v[176:179], v[244:247], v[64:67]
	s_barrier
	s_setprio 0
	ds_read_b128 v[188:191], v151 offset:16384
	ds_read_b128 v[220:223], v151 offset:17408
	ds_read_b128 v[224:227], v151 offset:18432
	ds_read_b128 v[228:231], v151 offset:19456
	ds_read_b128 v[232:235], v151 offset:20480
	ds_read_b128 v[236:239], v151 offset:21504
	ds_read_b128 v[240:243], v151 offset:22528
	ds_read_b128 v[244:247], v151 offset:23552
	s_add_i32 s84, s84, 2
	s_add_u32 s78, s78, 0x100
	s_addc_u32 s79, s79, 0
	s_add_u32 s69, s69, 0x100
	s_addc_u32 s71, s71, 0
	s_add_i32 s85, s85, s10
	s_mov_b32 m0, s85
	v_lshl_add_u64 v[180:181], s[80:81], 0, v[98:99]
	global_load_lds_dwordx4 v[180:181], off
	s_add_i32 m0, s85, 0x2000
	s_add_u32 s86, s80, 0x40000
	v_lshl_add_u64 v[192:193], s[80:81], 0, v[134:135]
	s_addc_u32 s87, s81, 0
	s_add_i32 s85, s88, s10
	global_load_lds_dwordx4 v[192:193], off
	v_lshl_add_u64 v[248:249], s[86:87], 0, v[98:99]
	s_mov_b32 m0, s85
	v_lshl_add_u64 v[250:251], s[82:83], 0, v[132:133]
	global_load_lds_dwordx4 v[248:249], off
	v_lshl_add_u64 v[248:249], s[86:87], 0, v[134:135]
	s_add_i32 m0, s85, 0x2000
	s_nop 0
	global_load_lds_dwordx4 v[248:249], off
	v_lshl_add_u64 v[248:249], s[82:83], 0, v[96:97]
	s_mov_b32 m0, s11
	s_nop 0
	global_load_lds_dwordx4 v[248:249], off
	s_mov_b32 m0, s20
	s_nop 0
	global_load_lds_dwordx4 v[250:251], off
	s_waitcnt vmcnt(8)
	s_waitcnt lgkmcnt(0)
	s_setprio 1
	s_barrier
	v_mfma_f32_16x16x32_bf16 v[60:63], v[140:143], v[188:191], 0
	v_mfma_f32_16x16x32_bf16 v[52:55], v[156:159], v[188:191], 0
	v_mfma_f32_16x16x32_bf16 v[44:47], v[140:143], v[224:227], 0
	v_mfma_f32_16x16x32_bf16 v[36:39], v[156:159], v[224:227], 0
	v_mfma_f32_16x16x32_bf16 v[28:31], v[140:143], v[232:235], 0
	v_mfma_f32_16x16x32_bf16 v[20:23], v[156:159], v[232:235], 0
	v_mfma_f32_16x16x32_bf16 v[12:15], v[140:143], v[240:243], 0
	v_mfma_f32_16x16x32_bf16 v[4:7], v[156:159], v[240:243], 0
	v_mfma_f32_16x16x32_bf16 v[60:63], v[152:155], v[220:223], v[60:63]
	v_mfma_f32_16x16x32_bf16 v[52:55], v[160:163], v[220:223], v[52:55]
	v_mfma_f32_16x16x32_bf16 v[44:47], v[152:155], v[228:231], v[44:47]
	v_mfma_f32_16x16x32_bf16 v[36:39], v[160:163], v[228:231], v[36:39]
	v_mfma_f32_16x16x32_bf16 v[28:31], v[152:155], v[236:239], v[28:31]
	v_mfma_f32_16x16x32_bf16 v[20:23], v[160:163], v[236:239], v[20:23]
	v_mfma_f32_16x16x32_bf16 v[12:15], v[152:155], v[244:247], v[12:15]
	v_mfma_f32_16x16x32_bf16 v[4:7], v[160:163], v[244:247], v[4:7]
	v_mfma_f32_16x16x32_bf16 v[56:59], v[164:167], v[188:191], 0
	v_mfma_f32_16x16x32_bf16 v[48:51], v[172:175], v[188:191], 0
	v_mfma_f32_16x16x32_bf16 v[40:43], v[164:167], v[224:227], 0
	v_mfma_f32_16x16x32_bf16 v[32:35], v[172:175], v[224:227], 0
	v_mfma_f32_16x16x32_bf16 v[24:27], v[164:167], v[232:235], 0
	v_mfma_f32_16x16x32_bf16 v[16:19], v[172:175], v[232:235], 0
	v_mfma_f32_16x16x32_bf16 v[8:11], v[164:167], v[240:243], 0
	v_mfma_f32_16x16x32_bf16 v[0:3], v[172:175], v[240:243], 0
	v_mfma_f32_16x16x32_bf16 v[56:59], v[168:171], v[220:223], v[56:59]
	v_mfma_f32_16x16x32_bf16 v[48:51], v[176:179], v[220:223], v[48:51]
	v_mfma_f32_16x16x32_bf16 v[40:43], v[168:171], v[228:231], v[40:43]
	v_mfma_f32_16x16x32_bf16 v[32:35], v[176:179], v[228:231], v[32:35]
	v_mfma_f32_16x16x32_bf16 v[24:27], v[168:171], v[236:239], v[24:27]
	v_mfma_f32_16x16x32_bf16 v[16:19], v[176:179], v[236:239], v[16:19]
	v_mfma_f32_16x16x32_bf16 v[8:11], v[168:171], v[244:247], v[8:11]
	v_mfma_f32_16x16x32_bf16 v[0:3], v[176:179], v[244:247], v[0:3]
	s_barrier
	s_setprio 0
	v_add_u32_e32 v160, 0x18000, v145
	v_add_u32_e32 v176, 0x1c000, v145
	ds_read_b128 v[140:143], v160
	ds_read_b128 v[152:155], v160 offset:1024
	ds_read_b128 v[156:159], v160 offset:2048
	ds_read_b128 v[160:163], v160 offset:3072
	ds_read_b128 v[164:167], v176
	ds_read_b128 v[168:171], v176 offset:1024
	ds_read_b128 v[172:175], v176 offset:2048
	ds_read_b128 v[176:179], v176 offset:3072
	s_add_i32 s85, 0, 0x18000
	s_add_i32 s86, 0, 0x1c000
	s_add_u32 s82, s82, 0x40000
	s_addc_u32 s83, s83, 0
	s_mov_b32 m0, s22
	v_lshl_add_u64 v[252:253], s[82:83], 0, v[96:97]
	ds_read_b128 v[188:191], v151 offset:32768
	ds_read_b128 v[220:223], v151 offset:33792
	ds_read_b128 v[224:227], v151 offset:34816
	ds_read_b128 v[228:231], v151 offset:35840
	ds_read_b128 v[232:235], v151 offset:36864
	ds_read_b128 v[236:239], v151 offset:37888
	ds_read_b128 v[240:243], v151 offset:38912
	ds_read_b128 v[244:247], v151 offset:39936
	global_load_lds_dwordx4 v[252:253], off
	v_lshl_add_u64 v[252:253], s[82:83], 0, v[132:133]
	s_mov_b32 m0, s23
	s_nop 0
	global_load_lds_dwordx4 v[252:253], off
	s_waitcnt vmcnt(8)
	s_waitcnt lgkmcnt(0)
	s_setprio 1
	s_barrier
	v_mfma_f32_16x16x32_bf16 v[128:131], v[140:143], v[188:191], v[128:131]
	v_mfma_f32_16x16x32_bf16 v[120:123], v[156:159], v[188:191], v[120:123]
	v_mfma_f32_16x16x32_bf16 v[112:115], v[140:143], v[224:227], v[112:115]
	v_mfma_f32_16x16x32_bf16 v[104:107], v[156:159], v[224:227], v[104:107]
	v_mfma_f32_16x16x32_bf16 v[92:95], v[140:143], v[232:235], v[92:95]
	v_mfma_f32_16x16x32_bf16 v[84:87], v[156:159], v[232:235], v[84:87]
	v_mfma_f32_16x16x32_bf16 v[76:79], v[140:143], v[240:243], v[76:79]
	v_mfma_f32_16x16x32_bf16 v[68:71], v[156:159], v[240:243], v[68:71]
	v_mfma_f32_16x16x32_bf16 v[128:131], v[152:155], v[220:223], v[128:131]
	v_mfma_f32_16x16x32_bf16 v[120:123], v[160:163], v[220:223], v[120:123]
	v_mfma_f32_16x16x32_bf16 v[112:115], v[152:155], v[228:231], v[112:115]
	v_mfma_f32_16x16x32_bf16 v[104:107], v[160:163], v[228:231], v[104:107]
	v_mfma_f32_16x16x32_bf16 v[92:95], v[152:155], v[236:239], v[92:95]
	v_mfma_f32_16x16x32_bf16 v[84:87], v[160:163], v[236:239], v[84:87]
	v_mfma_f32_16x16x32_bf16 v[76:79], v[152:155], v[244:247], v[76:79]
	v_mfma_f32_16x16x32_bf16 v[68:71], v[160:163], v[244:247], v[68:71]
	v_mfma_f32_16x16x32_bf16 v[124:127], v[164:167], v[188:191], v[124:127]
	v_mfma_f32_16x16x32_bf16 v[116:119], v[172:175], v[188:191], v[116:119]
	v_mfma_f32_16x16x32_bf16 v[108:111], v[164:167], v[224:227], v[108:111]
	v_mfma_f32_16x16x32_bf16 v[100:103], v[172:175], v[224:227], v[100:103]
	v_mfma_f32_16x16x32_bf16 v[88:91], v[164:167], v[232:235], v[88:91]
	v_mfma_f32_16x16x32_bf16 v[80:83], v[172:175], v[232:235], v[80:83]
	v_mfma_f32_16x16x32_bf16 v[72:75], v[164:167], v[240:243], v[72:75]
	v_mfma_f32_16x16x32_bf16 v[64:67], v[172:175], v[240:243], v[64:67]
	v_mfma_f32_16x16x32_bf16 v[124:127], v[168:171], v[220:223], v[124:127]
	v_mfma_f32_16x16x32_bf16 v[116:119], v[176:179], v[220:223], v[116:119]
	v_mfma_f32_16x16x32_bf16 v[108:111], v[168:171], v[228:231], v[108:111]
	v_mfma_f32_16x16x32_bf16 v[100:103], v[176:179], v[228:231], v[100:103]
	v_mfma_f32_16x16x32_bf16 v[88:91], v[168:171], v[236:239], v[88:91]
	v_mfma_f32_16x16x32_bf16 v[80:83], v[176:179], v[236:239], v[80:83]
	v_mfma_f32_16x16x32_bf16 v[72:75], v[168:171], v[244:247], v[72:75]
	v_mfma_f32_16x16x32_bf16 v[64:67], v[176:179], v[244:247], v[64:67]
	s_barrier
	s_setprio 0
	ds_read_b128 v[188:191], v151 offset:49152
	ds_read_b128 v[220:223], v151 offset:50176
	ds_read_b128 v[224:227], v151 offset:51200
	ds_read_b128 v[228:231], v151 offset:52224
	ds_read_b128 v[232:235], v151 offset:53248
	ds_read_b128 v[236:239], v151 offset:54272
	ds_read_b128 v[240:243], v151 offset:55296
	ds_read_b128 v[244:247], v151 offset:56320
	s_add_i32 s82, s85, s10
	s_mov_b32 m0, s82
	v_lshl_add_u64 v[180:181], v[180:181], 0, s[58:59]
	global_load_lds_dwordx4 v[180:181], off
	s_add_i32 m0, s82, 0x2000
	s_add_u32 s80, s80, 0x40080
	v_lshl_add_u64 v[180:181], v[192:193], 0, s[58:59]
	s_addc_u32 s81, s81, 0
	s_add_i32 s82, s86, s10
	global_load_lds_dwordx4 v[180:181], off
	v_lshl_add_u64 v[180:181], s[80:81], 0, v[98:99]
	s_mov_b32 m0, s82
	s_nop 0
	global_load_lds_dwordx4 v[180:181], off
	v_lshl_add_u64 v[180:181], s[80:81], 0, v[134:135]
	s_add_i32 m0, s82, 0x2000
	s_nop 0
	global_load_lds_dwordx4 v[180:181], off
	v_lshl_add_u64 v[180:181], v[248:249], 0, s[58:59]
	s_mov_b32 m0, s33
	s_nop 0
	global_load_lds_dwordx4 v[180:181], off
	v_lshl_add_u64 v[180:181], v[250:251], 0, s[58:59]
	s_mov_b32 m0, s43
	s_nop 0
	global_load_lds_dwordx4 v[180:181], off
	s_waitcnt vmcnt(8)
	s_waitcnt lgkmcnt(0)
	s_setprio 1
	s_barrier
	v_mfma_f32_16x16x32_bf16 v[60:63], v[140:143], v[188:191], v[60:63]
	v_mfma_f32_16x16x32_bf16 v[52:55], v[156:159], v[188:191], v[52:55]
	v_mfma_f32_16x16x32_bf16 v[44:47], v[140:143], v[224:227], v[44:47]
	v_mfma_f32_16x16x32_bf16 v[36:39], v[156:159], v[224:227], v[36:39]
	v_mfma_f32_16x16x32_bf16 v[28:31], v[140:143], v[232:235], v[28:31]
	v_mfma_f32_16x16x32_bf16 v[20:23], v[156:159], v[232:235], v[20:23]
	v_mfma_f32_16x16x32_bf16 v[12:15], v[140:143], v[240:243], v[12:15]
	v_mfma_f32_16x16x32_bf16 v[4:7], v[156:159], v[240:243], v[4:7]
	v_mfma_f32_16x16x32_bf16 v[60:63], v[152:155], v[220:223], v[60:63]
	v_mfma_f32_16x16x32_bf16 v[52:55], v[160:163], v[220:223], v[52:55]
	v_mfma_f32_16x16x32_bf16 v[44:47], v[152:155], v[228:231], v[44:47]
	v_mfma_f32_16x16x32_bf16 v[36:39], v[160:163], v[228:231], v[36:39]
	v_mfma_f32_16x16x32_bf16 v[28:31], v[152:155], v[236:239], v[28:31]
	v_mfma_f32_16x16x32_bf16 v[20:23], v[160:163], v[236:239], v[20:23]
	v_mfma_f32_16x16x32_bf16 v[12:15], v[152:155], v[244:247], v[12:15]
	v_mfma_f32_16x16x32_bf16 v[4:7], v[160:163], v[244:247], v[4:7]
	v_mfma_f32_16x16x32_bf16 v[56:59], v[164:167], v[188:191], v[56:59]
	v_mfma_f32_16x16x32_bf16 v[48:51], v[172:175], v[188:191], v[48:51]
	v_mfma_f32_16x16x32_bf16 v[40:43], v[164:167], v[224:227], v[40:43]
	v_mfma_f32_16x16x32_bf16 v[32:35], v[172:175], v[224:227], v[32:35]
	v_mfma_f32_16x16x32_bf16 v[24:27], v[164:167], v[232:235], v[24:27]
	v_mfma_f32_16x16x32_bf16 v[16:19], v[172:175], v[232:235], v[16:19]
	v_mfma_f32_16x16x32_bf16 v[8:11], v[164:167], v[240:243], v[8:11]
	v_mfma_f32_16x16x32_bf16 v[0:3], v[172:175], v[240:243], v[0:3]
	v_mfma_f32_16x16x32_bf16 v[56:59], v[168:171], v[220:223], v[56:59]
	v_mfma_f32_16x16x32_bf16 v[48:51], v[176:179], v[220:223], v[48:51]
	v_mfma_f32_16x16x32_bf16 v[40:43], v[168:171], v[228:231], v[40:43]
	v_mfma_f32_16x16x32_bf16 v[32:35], v[176:179], v[228:231], v[32:35]
	v_mfma_f32_16x16x32_bf16 v[24:27], v[168:171], v[236:239], v[24:27]
	v_mfma_f32_16x16x32_bf16 v[16:19], v[176:179], v[236:239], v[16:19]
	v_mfma_f32_16x16x32_bf16 v[8:11], v[168:171], v[244:247], v[8:11]
	v_mfma_f32_16x16x32_bf16 v[0:3], v[176:179], v[244:247], v[0:3]
	s_barrier
	s_setprio 0
	s_cmp_gt_u32 s84, 13
	s_cbranch_scc1 .Lpeel_exit_346
.LBB0_346:
	v_add_u32_e32 v160, 0x10000, v145
	v_add_u32_e32 v176, 0x14000, v145
	ds_read_b128 v[140:143], v160
	ds_read_b128 v[152:155], v160 offset:1024
	ds_read_b128 v[156:159], v160 offset:2048
	ds_read_b128 v[160:163], v160 offset:3072
	ds_read_b128 v[164:167], v176
	ds_read_b128 v[168:171], v176 offset:1024
	ds_read_b128 v[172:175], v176 offset:2048
	ds_read_b128 v[176:179], v176 offset:3072
	s_add_u32 s80, s78, 0xfffc0080
	s_addc_u32 s81, s79, -1
	s_add_i32 s85, 0, 0x10000
	s_cmp_eq_u32 s84, 12
	s_cselect_b32 s83, s27, s81
	s_cselect_b32 s82, s42, s80
	s_cselect_b32 s81, s56, s71
	s_cselect_b32 s80, s57, s69
	s_add_i32 s88, 0, 0x14000
	v_lshl_add_u64 v[180:181], s[78:79], 0, v[136:137]
	s_add_i32 m0, s11, 0xc000
	ds_read_b128 v[188:191], v151
	ds_read_b128 v[220:223], v151 offset:1024
	ds_read_b128 v[224:227], v151 offset:2048
	ds_read_b128 v[228:231], v151 offset:3072
	ds_read_b128 v[232:235], v151 offset:4096
	ds_read_b128 v[236:239], v151 offset:5120
	ds_read_b128 v[240:243], v151 offset:6144
	ds_read_b128 v[244:247], v151 offset:7168
	global_load_lds_dwordx4 v[180:181], off
	v_lshl_add_u64 v[180:181], s[78:79], 0, v[138:139]
	s_add_i32 m0, s11, 0xe000
	s_nop 0
	global_load_lds_dwordx4 v[180:181], off
	s_waitcnt vmcnt(8)
	s_waitcnt lgkmcnt(0)
	s_setprio 1
	s_barrier
	v_mfma_f32_16x16x32_bf16 v[128:131], v[140:143], v[188:191], v[128:131]
	v_mfma_f32_16x16x32_bf16 v[120:123], v[156:159], v[188:191], v[120:123]
	v_mfma_f32_16x16x32_bf16 v[112:115], v[140:143], v[224:227], v[112:115]
	v_mfma_f32_16x16x32_bf16 v[104:107], v[156:159], v[224:227], v[104:107]
	v_mfma_f32_16x16x32_bf16 v[92:95], v[140:143], v[232:235], v[92:95]
	v_mfma_f32_16x16x32_bf16 v[84:87], v[156:159], v[232:235], v[84:87]
	v_mfma_f32_16x16x32_bf16 v[76:79], v[140:143], v[240:243], v[76:79]
	v_mfma_f32_16x16x32_bf16 v[68:71], v[156:159], v[240:243], v[68:71]
	v_mfma_f32_16x16x32_bf16 v[128:131], v[152:155], v[220:223], v[128:131]
	v_mfma_f32_16x16x32_bf16 v[120:123], v[160:163], v[220:223], v[120:123]
	v_mfma_f32_16x16x32_bf16 v[112:115], v[152:155], v[228:231], v[112:115]
	v_mfma_f32_16x16x32_bf16 v[104:107], v[160:163], v[228:231], v[104:107]
	v_mfma_f32_16x16x32_bf16 v[92:95], v[152:155], v[236:239], v[92:95]
	v_mfma_f32_16x16x32_bf16 v[84:87], v[160:163], v[236:239], v[84:87]
	v_mfma_f32_16x16x32_bf16 v[76:79], v[152:155], v[244:247], v[76:79]
	v_mfma_f32_16x16x32_bf16 v[68:71], v[160:163], v[244:247], v[68:71]
	v_mfma_f32_16x16x32_bf16 v[124:127], v[164:167], v[188:191], v[124:127]
	v_mfma_f32_16x16x32_bf16 v[116:119], v[172:175], v[188:191], v[116:119]
	v_mfma_f32_16x16x32_bf16 v[108:111], v[164:167], v[224:227], v[108:111]
	v_mfma_f32_16x16x32_bf16 v[100:103], v[172:175], v[224:227], v[100:103]
	v_mfma_f32_16x16x32_bf16 v[88:91], v[164:167], v[232:235], v[88:91]
	v_mfma_f32_16x16x32_bf16 v[80:83], v[172:175], v[232:235], v[80:83]
	v_mfma_f32_16x16x32_bf16 v[72:75], v[164:167], v[240:243], v[72:75]
	v_mfma_f32_16x16x32_bf16 v[64:67], v[172:175], v[240:243], v[64:67]
	v_mfma_f32_16x16x32_bf16 v[124:127], v[168:171], v[220:223], v[124:127]
	v_mfma_f32_16x16x32_bf16 v[116:119], v[176:179], v[220:223], v[116:119]
	v_mfma_f32_16x16x32_bf16 v[108:111], v[168:171], v[228:231], v[108:111]
	v_mfma_f32_16x16x32_bf16 v[100:103], v[176:179], v[228:231], v[100:103]
	v_mfma_f32_16x16x32_bf16 v[88:91], v[168:171], v[236:239], v[88:91]
	v_mfma_f32_16x16x32_bf16 v[80:83], v[176:179], v[236:239], v[80:83]
	v_mfma_f32_16x16x32_bf16 v[72:75], v[168:171], v[244:247], v[72:75]
	v_mfma_f32_16x16x32_bf16 v[64:67], v[176:179], v[244:247], v[64:67]
	s_barrier
	s_setprio 0
	ds_read_b128 v[188:191], v151 offset:16384
	ds_read_b128 v[220:223], v151 offset:17408
	ds_read_b128 v[224:227], v151 offset:18432
	ds_read_b128 v[228:231], v151 offset:19456
	ds_read_b128 v[232:235], v151 offset:20480
	ds_read_b128 v[236:239], v151 offset:21504
	ds_read_b128 v[240:243], v151 offset:22528
	ds_read_b128 v[244:247], v151 offset:23552
	s_add_i32 s84, s84, 2
	s_add_u32 s78, s78, 0x100
	s_addc_u32 s79, s79, 0
	s_add_u32 s69, s69, 0x100
	s_addc_u32 s71, s71, 0
	s_add_i32 s85, s85, s10
	s_mov_b32 m0, s85
	v_lshl_add_u64 v[180:181], s[80:81], 0, v[98:99]
	global_load_lds_dwordx4 v[180:181], off
	s_add_i32 m0, s85, 0x2000
	s_add_u32 s86, s80, 0x40000
	v_lshl_add_u64 v[192:193], s[80:81], 0, v[134:135]
	s_addc_u32 s87, s81, 0
	s_add_i32 s85, s88, s10
	global_load_lds_dwordx4 v[192:193], off
	v_lshl_add_u64 v[248:249], s[86:87], 0, v[98:99]
	s_mov_b32 m0, s85
	v_lshl_add_u64 v[250:251], s[82:83], 0, v[132:133]
	global_load_lds_dwordx4 v[248:249], off
	v_lshl_add_u64 v[248:249], s[86:87], 0, v[134:135]
	s_add_i32 m0, s85, 0x2000
	s_nop 0
	global_load_lds_dwordx4 v[248:249], off
	v_lshl_add_u64 v[248:249], s[82:83], 0, v[96:97]
	s_mov_b32 m0, s11
	s_nop 0
	global_load_lds_dwordx4 v[248:249], off
	s_mov_b32 m0, s20
	s_nop 0
	global_load_lds_dwordx4 v[250:251], off
	s_waitcnt vmcnt(8)
	s_waitcnt lgkmcnt(0)
	s_setprio 1
	s_barrier
	v_mfma_f32_16x16x32_bf16 v[60:63], v[140:143], v[188:191], v[60:63]
	v_mfma_f32_16x16x32_bf16 v[52:55], v[156:159], v[188:191], v[52:55]
	v_mfma_f32_16x16x32_bf16 v[44:47], v[140:143], v[224:227], v[44:47]
	v_mfma_f32_16x16x32_bf16 v[36:39], v[156:159], v[224:227], v[36:39]
	v_mfma_f32_16x16x32_bf16 v[28:31], v[140:143], v[232:235], v[28:31]
	v_mfma_f32_16x16x32_bf16 v[20:23], v[156:159], v[232:235], v[20:23]
	v_mfma_f32_16x16x32_bf16 v[12:15], v[140:143], v[240:243], v[12:15]
	v_mfma_f32_16x16x32_bf16 v[4:7], v[156:159], v[240:243], v[4:7]
	v_mfma_f32_16x16x32_bf16 v[60:63], v[152:155], v[220:223], v[60:63]
	v_mfma_f32_16x16x32_bf16 v[52:55], v[160:163], v[220:223], v[52:55]
	v_mfma_f32_16x16x32_bf16 v[44:47], v[152:155], v[228:231], v[44:47]
	v_mfma_f32_16x16x32_bf16 v[36:39], v[160:163], v[228:231], v[36:39]
	v_mfma_f32_16x16x32_bf16 v[28:31], v[152:155], v[236:239], v[28:31]
	v_mfma_f32_16x16x32_bf16 v[20:23], v[160:163], v[236:239], v[20:23]
	v_mfma_f32_16x16x32_bf16 v[12:15], v[152:155], v[244:247], v[12:15]
	v_mfma_f32_16x16x32_bf16 v[4:7], v[160:163], v[244:247], v[4:7]
	v_mfma_f32_16x16x32_bf16 v[56:59], v[164:167], v[188:191], v[56:59]
	v_mfma_f32_16x16x32_bf16 v[48:51], v[172:175], v[188:191], v[48:51]
	v_mfma_f32_16x16x32_bf16 v[40:43], v[164:167], v[224:227], v[40:43]
	v_mfma_f32_16x16x32_bf16 v[32:35], v[172:175], v[224:227], v[32:35]
	v_mfma_f32_16x16x32_bf16 v[24:27], v[164:167], v[232:235], v[24:27]
	v_mfma_f32_16x16x32_bf16 v[16:19], v[172:175], v[232:235], v[16:19]
	v_mfma_f32_16x16x32_bf16 v[8:11], v[164:167], v[240:243], v[8:11]
	v_mfma_f32_16x16x32_bf16 v[0:3], v[172:175], v[240:243], v[0:3]
	v_mfma_f32_16x16x32_bf16 v[56:59], v[168:171], v[220:223], v[56:59]
	v_mfma_f32_16x16x32_bf16 v[48:51], v[176:179], v[220:223], v[48:51]
	v_mfma_f32_16x16x32_bf16 v[40:43], v[168:171], v[228:231], v[40:43]
	v_mfma_f32_16x16x32_bf16 v[32:35], v[176:179], v[228:231], v[32:35]
	v_mfma_f32_16x16x32_bf16 v[24:27], v[168:171], v[236:239], v[24:27]
	v_mfma_f32_16x16x32_bf16 v[16:19], v[176:179], v[236:239], v[16:19]
	v_mfma_f32_16x16x32_bf16 v[8:11], v[168:171], v[244:247], v[8:11]
	v_mfma_f32_16x16x32_bf16 v[0:3], v[176:179], v[244:247], v[0:3]
	s_barrier
	s_setprio 0
	v_add_u32_e32 v160, 0x18000, v145
	v_add_u32_e32 v176, 0x1c000, v145
	ds_read_b128 v[140:143], v160
	ds_read_b128 v[152:155], v160 offset:1024
	ds_read_b128 v[156:159], v160 offset:2048
	ds_read_b128 v[160:163], v160 offset:3072
	ds_read_b128 v[164:167], v176
	ds_read_b128 v[168:171], v176 offset:1024
	ds_read_b128 v[172:175], v176 offset:2048
	ds_read_b128 v[176:179], v176 offset:3072
	s_add_i32 s85, 0, 0x18000
	s_add_i32 s86, 0, 0x1c000
	s_add_u32 s82, s82, 0x40000
	s_addc_u32 s83, s83, 0
	s_mov_b32 m0, s22
	v_lshl_add_u64 v[252:253], s[82:83], 0, v[96:97]
	ds_read_b128 v[188:191], v151 offset:32768
	ds_read_b128 v[220:223], v151 offset:33792
	ds_read_b128 v[224:227], v151 offset:34816
	ds_read_b128 v[228:231], v151 offset:35840
	ds_read_b128 v[232:235], v151 offset:36864
	ds_read_b128 v[236:239], v151 offset:37888
	ds_read_b128 v[240:243], v151 offset:38912
	ds_read_b128 v[244:247], v151 offset:39936
	global_load_lds_dwordx4 v[252:253], off
	v_lshl_add_u64 v[252:253], s[82:83], 0, v[132:133]
	s_mov_b32 m0, s23
	s_nop 0
	global_load_lds_dwordx4 v[252:253], off
	s_waitcnt vmcnt(8)
	s_waitcnt lgkmcnt(0)
	s_setprio 1
	s_barrier
	v_mfma_f32_16x16x32_bf16 v[128:131], v[140:143], v[188:191], v[128:131]
	v_mfma_f32_16x16x32_bf16 v[120:123], v[156:159], v[188:191], v[120:123]
	v_mfma_f32_16x16x32_bf16 v[112:115], v[140:143], v[224:227], v[112:115]
	v_mfma_f32_16x16x32_bf16 v[104:107], v[156:159], v[224:227], v[104:107]
	v_mfma_f32_16x16x32_bf16 v[92:95], v[140:143], v[232:235], v[92:95]
	v_mfma_f32_16x16x32_bf16 v[84:87], v[156:159], v[232:235], v[84:87]
	v_mfma_f32_16x16x32_bf16 v[76:79], v[140:143], v[240:243], v[76:79]
	v_mfma_f32_16x16x32_bf16 v[68:71], v[156:159], v[240:243], v[68:71]
	v_mfma_f32_16x16x32_bf16 v[128:131], v[152:155], v[220:223], v[128:131]
	v_mfma_f32_16x16x32_bf16 v[120:123], v[160:163], v[220:223], v[120:123]
	v_mfma_f32_16x16x32_bf16 v[112:115], v[152:155], v[228:231], v[112:115]
	v_mfma_f32_16x16x32_bf16 v[104:107], v[160:163], v[228:231], v[104:107]
	v_mfma_f32_16x16x32_bf16 v[92:95], v[152:155], v[236:239], v[92:95]
	v_mfma_f32_16x16x32_bf16 v[84:87], v[160:163], v[236:239], v[84:87]
	v_mfma_f32_16x16x32_bf16 v[76:79], v[152:155], v[244:247], v[76:79]
	v_mfma_f32_16x16x32_bf16 v[68:71], v[160:163], v[244:247], v[68:71]
	v_mfma_f32_16x16x32_bf16 v[124:127], v[164:167], v[188:191], v[124:127]
	v_mfma_f32_16x16x32_bf16 v[116:119], v[172:175], v[188:191], v[116:119]
	v_mfma_f32_16x16x32_bf16 v[108:111], v[164:167], v[224:227], v[108:111]
	v_mfma_f32_16x16x32_bf16 v[100:103], v[172:175], v[224:227], v[100:103]
	v_mfma_f32_16x16x32_bf16 v[88:91], v[164:167], v[232:235], v[88:91]
	v_mfma_f32_16x16x32_bf16 v[80:83], v[172:175], v[232:235], v[80:83]
	v_mfma_f32_16x16x32_bf16 v[72:75], v[164:167], v[240:243], v[72:75]
	v_mfma_f32_16x16x32_bf16 v[64:67], v[172:175], v[240:243], v[64:67]
	v_mfma_f32_16x16x32_bf16 v[124:127], v[168:171], v[220:223], v[124:127]
	v_mfma_f32_16x16x32_bf16 v[116:119], v[176:179], v[220:223], v[116:119]
	v_mfma_f32_16x16x32_bf16 v[108:111], v[168:171], v[228:231], v[108:111]
	v_mfma_f32_16x16x32_bf16 v[100:103], v[176:179], v[228:231], v[100:103]
	v_mfma_f32_16x16x32_bf16 v[88:91], v[168:171], v[236:239], v[88:91]
	v_mfma_f32_16x16x32_bf16 v[80:83], v[176:179], v[236:239], v[80:83]
	v_mfma_f32_16x16x32_bf16 v[72:75], v[168:171], v[244:247], v[72:75]
	v_mfma_f32_16x16x32_bf16 v[64:67], v[176:179], v[244:247], v[64:67]
	s_barrier
	s_setprio 0
	ds_read_b128 v[188:191], v151 offset:49152
	ds_read_b128 v[220:223], v151 offset:50176
	ds_read_b128 v[224:227], v151 offset:51200
	ds_read_b128 v[228:231], v151 offset:52224
	ds_read_b128 v[232:235], v151 offset:53248
	ds_read_b128 v[236:239], v151 offset:54272
	ds_read_b128 v[240:243], v151 offset:55296
	ds_read_b128 v[244:247], v151 offset:56320
	s_add_i32 s82, s85, s10
	s_mov_b32 m0, s82
	v_lshl_add_u64 v[180:181], v[180:181], 0, s[58:59]
	global_load_lds_dwordx4 v[180:181], off
	s_add_i32 m0, s82, 0x2000
	s_add_u32 s80, s80, 0x40080
	v_lshl_add_u64 v[180:181], v[192:193], 0, s[58:59]
	s_addc_u32 s81, s81, 0
	s_add_i32 s82, s86, s10
	global_load_lds_dwordx4 v[180:181], off
	v_lshl_add_u64 v[180:181], s[80:81], 0, v[98:99]
	s_mov_b32 m0, s82
	s_nop 0
	global_load_lds_dwordx4 v[180:181], off
	v_lshl_add_u64 v[180:181], s[80:81], 0, v[134:135]
	s_add_i32 m0, s82, 0x2000
	s_nop 0
	global_load_lds_dwordx4 v[180:181], off
	v_lshl_add_u64 v[180:181], v[248:249], 0, s[58:59]
	s_mov_b32 m0, s33
	s_nop 0
	global_load_lds_dwordx4 v[180:181], off
	v_lshl_add_u64 v[180:181], v[250:251], 0, s[58:59]
	s_mov_b32 m0, s43
	s_nop 0
	global_load_lds_dwordx4 v[180:181], off
	s_waitcnt vmcnt(8)
	s_waitcnt lgkmcnt(0)
	s_setprio 1
	s_barrier
	v_mfma_f32_16x16x32_bf16 v[60:63], v[140:143], v[188:191], v[60:63]
	v_mfma_f32_16x16x32_bf16 v[52:55], v[156:159], v[188:191], v[52:55]
	v_mfma_f32_16x16x32_bf16 v[44:47], v[140:143], v[224:227], v[44:47]
	v_mfma_f32_16x16x32_bf16 v[36:39], v[156:159], v[224:227], v[36:39]
	v_mfma_f32_16x16x32_bf16 v[28:31], v[140:143], v[232:235], v[28:31]
	v_mfma_f32_16x16x32_bf16 v[20:23], v[156:159], v[232:235], v[20:23]
	v_mfma_f32_16x16x32_bf16 v[12:15], v[140:143], v[240:243], v[12:15]
	v_mfma_f32_16x16x32_bf16 v[4:7], v[156:159], v[240:243], v[4:7]
	v_mfma_f32_16x16x32_bf16 v[60:63], v[152:155], v[220:223], v[60:63]
	v_mfma_f32_16x16x32_bf16 v[52:55], v[160:163], v[220:223], v[52:55]
	v_mfma_f32_16x16x32_bf16 v[44:47], v[152:155], v[228:231], v[44:47]
	v_mfma_f32_16x16x32_bf16 v[36:39], v[160:163], v[228:231], v[36:39]
	v_mfma_f32_16x16x32_bf16 v[28:31], v[152:155], v[236:239], v[28:31]
	v_mfma_f32_16x16x32_bf16 v[20:23], v[160:163], v[236:239], v[20:23]
	v_mfma_f32_16x16x32_bf16 v[12:15], v[152:155], v[244:247], v[12:15]
	v_mfma_f32_16x16x32_bf16 v[4:7], v[160:163], v[244:247], v[4:7]
	v_mfma_f32_16x16x32_bf16 v[56:59], v[164:167], v[188:191], v[56:59]
	v_mfma_f32_16x16x32_bf16 v[48:51], v[172:175], v[188:191], v[48:51]
	v_mfma_f32_16x16x32_bf16 v[40:43], v[164:167], v[224:227], v[40:43]
	v_mfma_f32_16x16x32_bf16 v[32:35], v[172:175], v[224:227], v[32:35]
	v_mfma_f32_16x16x32_bf16 v[24:27], v[164:167], v[232:235], v[24:27]
	v_mfma_f32_16x16x32_bf16 v[16:19], v[172:175], v[232:235], v[16:19]
	v_mfma_f32_16x16x32_bf16 v[8:11], v[164:167], v[240:243], v[8:11]
	v_mfma_f32_16x16x32_bf16 v[0:3], v[172:175], v[240:243], v[0:3]
	v_mfma_f32_16x16x32_bf16 v[56:59], v[168:171], v[220:223], v[56:59]
	v_mfma_f32_16x16x32_bf16 v[48:51], v[176:179], v[220:223], v[48:51]
	v_mfma_f32_16x16x32_bf16 v[40:43], v[168:171], v[228:231], v[40:43]
	v_mfma_f32_16x16x32_bf16 v[32:35], v[176:179], v[228:231], v[32:35]
	v_mfma_f32_16x16x32_bf16 v[24:27], v[168:171], v[236:239], v[24:27]
	v_mfma_f32_16x16x32_bf16 v[16:19], v[176:179], v[236:239], v[16:19]
	v_mfma_f32_16x16x32_bf16 v[8:11], v[168:171], v[244:247], v[8:11]
	v_mfma_f32_16x16x32_bf16 v[0:3], v[176:179], v[244:247], v[0:3]
	s_barrier
	s_setprio 0
	s_cmp_gt_u32 s84, 13
	s_cbranch_scc0 .LBB0_346
